# GEMM K-loops: s_setprio 1 moved before the pre-MFMA barrier, the redundant post-barrier lgkmcnt(0) removed, s_setprio 0 moved after the post-MFMA barrier (three fewer issue slots on each barrier-to-MF
# speedup vs baseline: 1.0062x; 1.0062x over previous
; #define PG8_STAGE(bufoff, gbase, voff) do { _Pragma("unroll") for (int _i = 0; _i < 2; ++_i) \
;         __builtin_amdgcn_global_load_lds((const unsigned*)((const char*)(gbase) + (voff)[_i]), (PG8_LAS unsigned*)(lds + (bufoff) + ldsw + _i * 8192), 16, 0, 0); } while (0)
; #define PG8_LDA(dst, b, h) do { _Pragma("unroll") for (int m = 0; m < 4; ++m) _Pragma("unroll") for (int k = 0; k < 2; ++k) dst[m][k] = *(const PG8_LAS bf16x8*)(lds + PG8_SA(b, h) + aoff + m * 2048 + k * 1024); } while (0)
; #define PG8_LDB(dst, b, h) do { _Pragma("unroll") for (int n = 0; n < 2; ++n) _Pragma("unroll") for (int k = 0; k < 2; ++k) dst[n][k] = *(const PG8_LAS bf16x8*)(lds + PG8_SB(b, h) + boff + n * 2048 + k * 1024); } while (0)
; #define PG8_MMA(ai, bj, At, Bt) do { __builtin_amdgcn_s_setprio(1); _Pragma("unroll") for (int m = 0; m < 4; ++m) _Pragma("unroll") for (int n = 0; n < 2; ++n) _Pragma("unroll") for (int k = 0; k < 2; ++k) \
;         acc[ai][bj][m][n] = __builtin_amdgcn_mfma_f32_16x16x32_bf16(Bt[n][k], At[m][k], acc[ai][bj][m][n], 0, 0, 0); __builtin_amdgcn_s_setprio(0); } while (0)
; #define PG8_WAIT_V(n) asm volatile("s_waitcnt vmcnt(" #n ")" ::: "memory")
; #define PG8_WAIT_L(n) asm volatile("s_waitcnt lgkmcnt(" #n ")" ::: "memory")
; #define PG8_BAR __builtin_amdgcn_s_barrier()
; #define PG8_SCHED __builtin_amdgcn_sched_barrier(0)
; template <class Epi, class Sched, bool ALIGN_EPI = false, bool SP2 = false>
; __device__ __forceinline__ void gemm_phase(PG8_LAS unsigned char* lds, const Gemm g, const Sched& S, const Epi& E) {
;     ...
;             PG8_LDB(B0, 0, 0); PG8_LDB(B1, 0, 1); PG8_SCHED; PG8_LDA(At, 0, 0); PG8_STAGE(PG8_SA(1, 1), a1 + hstep, voffA);
;             PG8_WAIT_V(8); PG8_WAIT_L(0); PG8_BAR; PG8_MMA(0, 0, At, B0); PG8_MMA(0, 1, At, B1); PG8_BAR; PG8_SCHED;
;             PG8_LDA(At, 0, 1); PG8_STAGE(PG8_SB(0, 0), b2, voffB); PG8_STAGE(PG8_SB(0, 1), b2 + hstepB, voffB); PG8_STAGE(PG8_SA(0, 0), a2, voffA);
.LBB0_150:
	ds_read_b128 v[156:159], v150
	ds_read_b128 v[160:163], v150 offset:1024
	ds_read_b128 v[164:167], v150 offset:2048
	ds_read_b128 v[168:171], v150 offset:3072
	ds_read_b128 v[172:175], v151
	ds_read_b128 v[176:179], v151 offset:1024
	ds_read_b128 v[180:183], v151 offset:2048
	ds_read_b128 v[184:187], v151 offset:3072
	s_add_u32 s26, s24, 0x4000
	s_addc_u32 s27, s25, 0
	s_cmp_eq_u32 s75, 12
	s_cselect_b32 s40, s71, s26
	s_cselect_b32 s41, s17, s27
	s_cselect_b32 s28, s72, s73
	s_cselect_b32 s29, s15, s74
	s_add_u32 s26, s40, 0x8000
	s_addc_u32 s27, s41, 0
	v_lshl_add_u64 v[216:217], s[24:25], 0, v[140:141]
	s_add_i32 m0, s23, 0xc000
	ds_read_b128 v[188:191], v152
	ds_read_b128 v[192:195], v152 offset:1024
	ds_read_b128 v[196:199], v152 offset:2048
	ds_read_b128 v[200:203], v152 offset:3072
	ds_read_b128 v[204:207], v152 offset:4096
	ds_read_b128 v[208:211], v152 offset:5120
	ds_read_b128 v[212:215], v152 offset:6144
	ds_read_b128 v[220:223], v152 offset:7168
	global_load_lds_dwordx4 v[216:217], off
	v_lshl_add_u64 v[216:217], s[24:25], 0, v[142:143]
	s_add_i32 m0, s23, 0xe000
	s_nop 0
	global_load_lds_dwordx4 v[216:217], off
	s_waitcnt vmcnt(8)
	s_waitcnt lgkmcnt(0)
	s_setprio 1
	s_barrier
	v_mfma_f32_16x16x32_bf16 v[126:129], v[156:159], v[188:191], v[126:129]
	v_mfma_f32_16x16x32_bf16 v[122:125], v[164:167], v[188:191], v[122:125]
	v_mfma_f32_16x16x32_bf16 v[114:117], v[156:159], v[196:199], v[114:117]
	v_mfma_f32_16x16x32_bf16 v[106:109], v[164:167], v[196:199], v[106:109]
	v_mfma_f32_16x16x32_bf16 v[98:101], v[156:159], v[204:207], v[98:101]
	v_mfma_f32_16x16x32_bf16 v[90:93], v[164:167], v[204:207], v[90:93]
	v_mfma_f32_16x16x32_bf16 v[78:81], v[156:159], v[212:215], v[78:81]
	v_mfma_f32_16x16x32_bf16 v[74:77], v[164:167], v[212:215], v[74:77]
	v_mfma_f32_16x16x32_bf16 v[126:129], v[160:163], v[192:195], v[126:129]
	v_mfma_f32_16x16x32_bf16 v[122:125], v[168:171], v[192:195], v[122:125]
	v_mfma_f32_16x16x32_bf16 v[114:117], v[160:163], v[200:203], v[114:117]
	v_mfma_f32_16x16x32_bf16 v[106:109], v[168:171], v[200:203], v[106:109]
	v_mfma_f32_16x16x32_bf16 v[98:101], v[160:163], v[208:211], v[98:101]
	v_mfma_f32_16x16x32_bf16 v[90:93], v[168:171], v[208:211], v[90:93]
	v_mfma_f32_16x16x32_bf16 v[78:81], v[160:163], v[220:223], v[78:81]
	v_mfma_f32_16x16x32_bf16 v[74:77], v[168:171], v[220:223], v[74:77]
	s_setprio 0
	s_setprio 1
	v_mfma_f32_16x16x32_bf16 v[118:121], v[172:175], v[188:191], v[118:121]
	v_mfma_f32_16x16x32_bf16 v[110:113], v[180:183], v[188:191], v[110:113]
	v_mfma_f32_16x16x32_bf16 v[102:105], v[172:175], v[196:199], v[102:105]
	v_mfma_f32_16x16x32_bf16 v[94:97], v[180:183], v[196:199], v[94:97]
	v_mfma_f32_16x16x32_bf16 v[86:89], v[172:175], v[204:207], v[86:89]
	v_mfma_f32_16x16x32_bf16 v[82:85], v[180:183], v[204:207], v[82:85]
	v_mfma_f32_16x16x32_bf16 v[70:73], v[172:175], v[212:215], v[70:73]
	v_mfma_f32_16x16x32_bf16 v[66:69], v[180:183], v[212:215], v[66:69]
	v_mfma_f32_16x16x32_bf16 v[118:121], v[176:179], v[192:195], v[118:121]
	v_mfma_f32_16x16x32_bf16 v[110:113], v[184:187], v[192:195], v[110:113]
	v_mfma_f32_16x16x32_bf16 v[102:105], v[176:179], v[200:203], v[102:105]
	v_mfma_f32_16x16x32_bf16 v[94:97], v[184:187], v[200:203], v[94:97]
	v_mfma_f32_16x16x32_bf16 v[86:89], v[176:179], v[208:211], v[86:89]
	v_mfma_f32_16x16x32_bf16 v[82:85], v[184:187], v[208:211], v[82:85]
	v_mfma_f32_16x16x32_bf16 v[70:73], v[176:179], v[220:223], v[70:73]
	v_mfma_f32_16x16x32_bf16 v[66:69], v[184:187], v[220:223], v[66:69]
	s_barrier
	s_setprio 0
	s_add_i32 s76, s56, s0
	v_lshl_add_u64 v[216:217], s[28:29], 0, v[134:135]
	s_mov_b32 m0, s76
	ds_read_b128 v[188:191], v152 offset:16384
	ds_read_b128 v[192:195], v152 offset:17408
	ds_read_b128 v[196:199], v152 offset:18432
	ds_read_b128 v[200:203], v152 offset:19456
	ds_read_b128 v[204:207], v152 offset:20480
	ds_read_b128 v[208:211], v152 offset:21504
	ds_read_b128 v[212:215], v152 offset:22528
	ds_read_b128 v[220:223], v152 offset:23552
	global_load_lds_dwordx4 v[216:217], off
	s_add_i32 m0, s76, 0x2000
	s_add_u32 s76, s28, 0x1000
	v_lshl_add_u64 v[216:217], s[28:29], 0, v[130:131]
	s_addc_u32 s77, s29, 0
	s_add_i32 s78, s57, s0
	global_load_lds_dwordx4 v[216:217], off
	v_lshl_add_u64 v[216:217], s[76:77], 0, v[134:135]
	s_mov_b32 m0, s78
	s_nop 0
	global_load_lds_dwordx4 v[216:217], off
	v_lshl_add_u64 v[216:217], s[76:77], 0, v[130:131]
	s_add_i32 m0, s78, 0x2000
	s_nop 0
	global_load_lds_dwordx4 v[216:217], off
	v_lshl_add_u64 v[216:217], s[40:41], 0, v[136:137]
	s_mov_b32 m0, s23
	s_nop 0
	global_load_lds_dwordx4 v[216:217], off
	v_lshl_add_u64 v[216:217], s[40:41], 0, v[132:133]
	s_mov_b32 m0, s49
	s_nop 0
	global_load_lds_dwordx4 v[216:217], off
	s_waitcnt vmcnt(8)
	s_waitcnt lgkmcnt(0)
	s_setprio 1
	s_barrier
; #define PG8_STAGE(bufoff, gbase, voff) do { _Pragma("unroll") for (int _i = 0; _i < 2; ++_i) \
;         __builtin_amdgcn_global_load_lds((const unsigned*)((const char*)(gbase) + (voff)[_i]), (PG8_LAS unsigned*)(lds + (bufoff) + ldsw + _i * 8192), 16, 0, 0); } while (0)
; #define PG8_LDA(dst, b, h) do { _Pragma("unroll") for (int m = 0; m < 4; ++m) _Pragma("unroll") for (int k = 0; k < 2; ++k) dst[m][k] = *(const PG8_LAS bf16x8*)(lds + PG8_SA(b, h) + aoff + m * 2048 + k * 1024); } while (0)
; #define PG8_LDB(dst, b, h) do { _Pragma("unroll") for (int n = 0; n < 2; ++n) _Pragma("unroll") for (int k = 0; k < 2; ++k) dst[n][k] = *(const PG8_LAS bf16x8*)(lds + PG8_SB(b, h) + boff + n * 2048 + k * 1024); } while (0)
; #define PG8_MMA(ai, bj, At, Bt) do { __builtin_amdgcn_s_setprio(1); _Pragma("unroll") for (int m = 0; m < 4; ++m) _Pragma("unroll") for (int n = 0; n < 2; ++n) _Pragma("unroll") for (int k = 0; k < 2; ++k) \
;         acc[ai][bj][m][n] = __builtin_amdgcn_mfma_f32_16x16x32_bf16(Bt[n][k], At[m][k], acc[ai][bj][m][n], 0, 0, 0); __builtin_amdgcn_s_setprio(0); } while (0)
; #define PG8_WAIT_V(n) asm volatile("s_waitcnt vmcnt(" #n ")" ::: "memory")
; #define PG8_WAIT_L(n) asm volatile("s_waitcnt lgkmcnt(" #n ")" ::: "memory")
; #define PG8_BAR __builtin_amdgcn_s_barrier()
; #define PG8_SCHED __builtin_amdgcn_sched_barrier(0)
; template <class Epi, class Sched, bool ALIGN_EPI = false, bool SP2 = false>
; __device__ __forceinline__ void gemm_phase(PG8_LAS unsigned char* lds, const Gemm g, const Sched& S, const Epi& E) {
;     ...
;             PG8_WAIT_V(8); PG8_WAIT_L(0); PG8_BAR; PG8_MMA(1, 0, At, B0); PG8_MMA(1, 1, At, B1); PG8_BAR; PG8_SCHED;
;             PG8_LDB(B0, 1, 0); PG8_LDB(B1, 1, 1); PG8_SCHED; PG8_LDA(At, 1, 0); PG8_STAGE(PG8_SA(0, 1), a2 + hstep, voffA);
;             PG8_WAIT_V(8); PG8_WAIT_L(0); PG8_BAR; PG8_MMA(0, 0, At, B0); PG8_MMA(0, 1, At, B1); PG8_BAR; PG8_SCHED;
	v_mfma_f32_16x16x32_bf16 v[62:65], v[156:159], v[188:191], v[62:65]
	v_mfma_f32_16x16x32_bf16 v[58:61], v[164:167], v[188:191], v[58:61]
	v_mfma_f32_16x16x32_bf16 v[46:49], v[156:159], v[196:199], v[46:49]
	v_mfma_f32_16x16x32_bf16 v[42:45], v[164:167], v[196:199], v[42:45]
	v_mfma_f32_16x16x32_bf16 v[34:37], v[156:159], v[204:207], v[34:37]
	v_mfma_f32_16x16x32_bf16 v[26:29], v[164:167], v[204:207], v[26:29]
	v_mfma_f32_16x16x32_bf16 v[18:21], v[156:159], v[212:215], v[18:21]
	v_mfma_f32_16x16x32_bf16 v[10:13], v[164:167], v[212:215], v[10:13]
	v_mfma_f32_16x16x32_bf16 v[62:65], v[160:163], v[192:195], v[62:65]
	v_mfma_f32_16x16x32_bf16 v[58:61], v[168:171], v[192:195], v[58:61]
	v_mfma_f32_16x16x32_bf16 v[46:49], v[160:163], v[200:203], v[46:49]
	v_mfma_f32_16x16x32_bf16 v[42:45], v[168:171], v[200:203], v[42:45]
	v_mfma_f32_16x16x32_bf16 v[34:37], v[160:163], v[208:211], v[34:37]
	v_mfma_f32_16x16x32_bf16 v[26:29], v[168:171], v[208:211], v[26:29]
	v_mfma_f32_16x16x32_bf16 v[18:21], v[160:163], v[220:223], v[18:21]
	v_mfma_f32_16x16x32_bf16 v[10:13], v[168:171], v[220:223], v[10:13]
	s_setprio 0
	s_setprio 1
	v_mfma_f32_16x16x32_bf16 v[54:57], v[172:175], v[188:191], v[54:57]
	v_mfma_f32_16x16x32_bf16 v[50:53], v[180:183], v[188:191], v[50:53]
	v_mfma_f32_16x16x32_bf16 v[38:41], v[172:175], v[196:199], v[38:41]
	v_mfma_f32_16x16x32_bf16 v[30:33], v[180:183], v[196:199], v[30:33]
	v_mfma_f32_16x16x32_bf16 v[22:25], v[172:175], v[204:207], v[22:25]
	v_mfma_f32_16x16x32_bf16 v[14:17], v[180:183], v[204:207], v[14:17]
	v_mfma_f32_16x16x32_bf16 v[6:9], v[172:175], v[212:215], v[6:9]
	v_mfma_f32_16x16x32_bf16 v[2:5], v[180:183], v[212:215], v[2:5]
	v_mfma_f32_16x16x32_bf16 v[54:57], v[176:179], v[192:195], v[54:57]
	v_mfma_f32_16x16x32_bf16 v[50:53], v[184:187], v[192:195], v[50:53]
	v_mfma_f32_16x16x32_bf16 v[38:41], v[176:179], v[200:203], v[38:41]
	v_mfma_f32_16x16x32_bf16 v[30:33], v[184:187], v[200:203], v[30:33]
	v_mfma_f32_16x16x32_bf16 v[22:25], v[176:179], v[208:211], v[22:25]
	v_mfma_f32_16x16x32_bf16 v[14:17], v[184:187], v[208:211], v[14:17]
	v_mfma_f32_16x16x32_bf16 v[6:9], v[176:179], v[220:223], v[6:9]
	v_mfma_f32_16x16x32_bf16 v[2:5], v[184:187], v[220:223], v[2:5]
	s_barrier
	s_setprio 0
	s_add_i32 s76, 0, 0x18000
	v_add_u32_e32 v148, s76, v149
	s_add_i32 s77, 0, 0x1c000
	ds_read_b128 v[156:159], v148
	ds_read_b128 v[160:163], v148 offset:1024
	ds_read_b128 v[164:167], v148 offset:2048
	ds_read_b128 v[168:171], v148 offset:3072
	v_add_u32_e32 v148, s77, v149
	ds_read_b128 v[172:175], v148
	ds_read_b128 v[176:179], v148 offset:1024
	ds_read_b128 v[180:183], v148 offset:2048
	ds_read_b128 v[184:187], v148 offset:3072
	s_add_u32 s40, s40, 0x4000
	s_addc_u32 s41, s41, 0
	s_mov_b32 m0, s50
	v_lshl_add_u64 v[216:217], s[40:41], 0, v[136:137]
	ds_read_b128 v[188:191], v152 offset:32768
	ds_read_b128 v[192:195], v152 offset:33792
	ds_read_b128 v[196:199], v152 offset:34816
	ds_read_b128 v[200:203], v152 offset:35840
	ds_read_b128 v[204:207], v152 offset:36864
	ds_read_b128 v[208:211], v152 offset:37888
	ds_read_b128 v[212:215], v152 offset:38912
	ds_read_b128 v[220:223], v152 offset:39936
	global_load_lds_dwordx4 v[216:217], off
	v_lshl_add_u64 v[216:217], s[40:41], 0, v[132:133]
	s_mov_b32 m0, s51
	s_nop 0
	global_load_lds_dwordx4 v[216:217], off
	s_waitcnt vmcnt(8)
	s_waitcnt lgkmcnt(0)
	s_setprio 1
	s_barrier
	v_mfma_f32_16x16x32_bf16 v[126:129], v[156:159], v[188:191], v[126:129]
	v_mfma_f32_16x16x32_bf16 v[122:125], v[164:167], v[188:191], v[122:125]
	v_mfma_f32_16x16x32_bf16 v[114:117], v[156:159], v[196:199], v[114:117]
	v_mfma_f32_16x16x32_bf16 v[106:109], v[164:167], v[196:199], v[106:109]
	v_mfma_f32_16x16x32_bf16 v[98:101], v[156:159], v[204:207], v[98:101]
	v_mfma_f32_16x16x32_bf16 v[90:93], v[164:167], v[204:207], v[90:93]
	v_mfma_f32_16x16x32_bf16 v[78:81], v[156:159], v[212:215], v[78:81]
	v_mfma_f32_16x16x32_bf16 v[74:77], v[164:167], v[212:215], v[74:77]
	v_mfma_f32_16x16x32_bf16 v[126:129], v[160:163], v[192:195], v[126:129]
	v_mfma_f32_16x16x32_bf16 v[122:125], v[168:171], v[192:195], v[122:125]
	v_mfma_f32_16x16x32_bf16 v[114:117], v[160:163], v[200:203], v[114:117]
	v_mfma_f32_16x16x32_bf16 v[106:109], v[168:171], v[200:203], v[106:109]
	v_mfma_f32_16x16x32_bf16 v[98:101], v[160:163], v[208:211], v[98:101]
	v_mfma_f32_16x16x32_bf16 v[90:93], v[168:171], v[208:211], v[90:93]
	v_mfma_f32_16x16x32_bf16 v[78:81], v[160:163], v[220:223], v[78:81]
	v_mfma_f32_16x16x32_bf16 v[74:77], v[168:171], v[220:223], v[74:77]
	s_setprio 0
	s_setprio 1
	v_mfma_f32_16x16x32_bf16 v[118:121], v[172:175], v[188:191], v[118:121]
	v_mfma_f32_16x16x32_bf16 v[110:113], v[180:183], v[188:191], v[110:113]
	v_mfma_f32_16x16x32_bf16 v[102:105], v[172:175], v[196:199], v[102:105]
	v_mfma_f32_16x16x32_bf16 v[94:97], v[180:183], v[196:199], v[94:97]
	v_mfma_f32_16x16x32_bf16 v[86:89], v[172:175], v[204:207], v[86:89]
	v_mfma_f32_16x16x32_bf16 v[82:85], v[180:183], v[204:207], v[82:85]
	v_mfma_f32_16x16x32_bf16 v[70:73], v[172:175], v[212:215], v[70:73]
	v_mfma_f32_16x16x32_bf16 v[66:69], v[180:183], v[212:215], v[66:69]
	v_mfma_f32_16x16x32_bf16 v[118:121], v[176:179], v[192:195], v[118:121]
	v_mfma_f32_16x16x32_bf16 v[110:113], v[184:187], v[192:195], v[110:113]
	v_mfma_f32_16x16x32_bf16 v[102:105], v[176:179], v[200:203], v[102:105]
	v_mfma_f32_16x16x32_bf16 v[94:97], v[184:187], v[200:203], v[94:97]
	v_mfma_f32_16x16x32_bf16 v[86:89], v[176:179], v[208:211], v[86:89]
	v_mfma_f32_16x16x32_bf16 v[82:85], v[184:187], v[208:211], v[82:85]
	v_mfma_f32_16x16x32_bf16 v[70:73], v[176:179], v[220:223], v[70:73]
	v_mfma_f32_16x16x32_bf16 v[66:69], v[184:187], v[220:223], v[66:69]
	s_barrier
; #define PG8_STAGE(bufoff, gbase, voff) do { _Pragma("unroll") for (int _i = 0; _i < 2; ++_i) \
;         __builtin_amdgcn_global_load_lds((const unsigned*)((const char*)(gbase) + (voff)[_i]), (PG8_LAS unsigned*)(lds + (bufoff) + ldsw + _i * 8192), 16, 0, 0); } while (0)
; #define PG8_LDA(dst, b, h) do { _Pragma("unroll") for (int m = 0; m < 4; ++m) _Pragma("unroll") for (int k = 0; k < 2; ++k) dst[m][k] = *(const PG8_LAS bf16x8*)(lds + PG8_SA(b, h) + aoff + m * 2048 + k * 1024); } while (0)
; #define PG8_MMA(ai, bj, At, Bt) do { __builtin_amdgcn_s_setprio(1); _Pragma("unroll") for (int m = 0; m < 4; ++m) _Pragma("unroll") for (int n = 0; n < 2; ++n) _Pragma("unroll") for (int k = 0; k < 2; ++k) \
;         acc[ai][bj][m][n] = __builtin_amdgcn_mfma_f32_16x16x32_bf16(Bt[n][k], At[m][k], acc[ai][bj][m][n], 0, 0, 0); __builtin_amdgcn_s_setprio(0); } while (0)
; #define PG8_WAIT_V(n) asm volatile("s_waitcnt vmcnt(" #n ")" ::: "memory")
; #define PG8_WAIT_L(n) asm volatile("s_waitcnt lgkmcnt(" #n ")" ::: "memory")
; #define PG8_BAR __builtin_amdgcn_s_barrier()
; #define PG8_SCHED __builtin_amdgcn_sched_barrier(0)
; template <class Epi, class Sched, bool ALIGN_EPI = false, bool SP2 = false>
; __device__ __forceinline__ void gemm_phase(PG8_LAS unsigned char* lds, const Gemm g, const Sched& S, const Epi& E) {
;     ...
;             PG8_LDA(At, 1, 1); PG8_STAGE(PG8_SB(1, 0), b3, voffB); PG8_STAGE(PG8_SB(1, 1), b3 + hstepB, voffB); PG8_STAGE(PG8_SA(1, 0), a3, voffA);
;             PG8_WAIT_V(8); PG8_WAIT_L(0); PG8_BAR; PG8_MMA(1, 0, At, B0); PG8_MMA(1, 1, At, B1); PG8_BAR; PG8_SCHED;
	s_setprio 0
	s_add_u32 s40, s28, 0x8000
	s_addc_u32 s41, s29, 0
	s_add_i32 s76, s76, s0
	v_lshl_add_u64 v[216:217], s[40:41], 0, v[134:135]
	s_mov_b32 m0, s76
	ds_read_b128 v[188:191], v152 offset:49152
	ds_read_b128 v[192:195], v152 offset:50176
	ds_read_b128 v[196:199], v152 offset:51200
	ds_read_b128 v[200:203], v152 offset:52224
	ds_read_b128 v[204:207], v152 offset:53248
	ds_read_b128 v[208:211], v152 offset:54272
	ds_read_b128 v[212:215], v152 offset:55296
	ds_read_b128 v[220:223], v152 offset:56320
	global_load_lds_dwordx4 v[216:217], off
	s_add_i32 m0, s76, 0x2000
	s_add_u32 s28, s28, 0x9000
	v_lshl_add_u64 v[216:217], s[40:41], 0, v[130:131]
	s_addc_u32 s29, s29, 0
	s_add_i32 s40, s77, s0
	global_load_lds_dwordx4 v[216:217], off
	v_lshl_add_u64 v[216:217], s[28:29], 0, v[134:135]
	s_mov_b32 m0, s40
	s_nop 0
	global_load_lds_dwordx4 v[216:217], off
	v_lshl_add_u64 v[216:217], s[28:29], 0, v[130:131]
	s_add_i32 m0, s40, 0x2000
	s_nop 0
	global_load_lds_dwordx4 v[216:217], off
	v_lshl_add_u64 v[216:217], s[26:27], 0, v[136:137]
	s_mov_b32 m0, s54
	s_nop 0
	global_load_lds_dwordx4 v[216:217], off
	v_lshl_add_u64 v[216:217], s[26:27], 0, v[132:133]
	s_mov_b32 m0, s55
	s_nop 0
	global_load_lds_dwordx4 v[216:217], off
	s_waitcnt vmcnt(8)
	s_waitcnt lgkmcnt(0)
	s_setprio 1
	s_barrier
	v_mfma_f32_16x16x32_bf16 v[62:65], v[156:159], v[188:191], v[62:65]
	v_mfma_f32_16x16x32_bf16 v[58:61], v[164:167], v[188:191], v[58:61]
	v_mfma_f32_16x16x32_bf16 v[46:49], v[156:159], v[196:199], v[46:49]
	v_mfma_f32_16x16x32_bf16 v[42:45], v[164:167], v[196:199], v[42:45]
	v_mfma_f32_16x16x32_bf16 v[34:37], v[156:159], v[204:207], v[34:37]
	v_mfma_f32_16x16x32_bf16 v[26:29], v[164:167], v[204:207], v[26:29]
	v_mfma_f32_16x16x32_bf16 v[18:21], v[156:159], v[212:215], v[18:21]
	v_mfma_f32_16x16x32_bf16 v[10:13], v[164:167], v[212:215], v[10:13]
	v_mfma_f32_16x16x32_bf16 v[62:65], v[160:163], v[192:195], v[62:65]
	v_mfma_f32_16x16x32_bf16 v[58:61], v[168:171], v[192:195], v[58:61]
	v_mfma_f32_16x16x32_bf16 v[46:49], v[160:163], v[200:203], v[46:49]
	v_mfma_f32_16x16x32_bf16 v[42:45], v[168:171], v[200:203], v[42:45]
	v_mfma_f32_16x16x32_bf16 v[34:37], v[160:163], v[208:211], v[34:37]
	v_mfma_f32_16x16x32_bf16 v[26:29], v[168:171], v[208:211], v[26:29]
	v_mfma_f32_16x16x32_bf16 v[18:21], v[160:163], v[220:223], v[18:21]
	v_mfma_f32_16x16x32_bf16 v[10:13], v[168:171], v[220:223], v[10:13]
	s_setprio 0
	s_setprio 1
	v_mfma_f32_16x16x32_bf16 v[54:57], v[172:175], v[188:191], v[54:57]
	v_mfma_f32_16x16x32_bf16 v[50:53], v[180:183], v[188:191], v[50:53]
	v_mfma_f32_16x16x32_bf16 v[38:41], v[172:175], v[196:199], v[38:41]
	v_mfma_f32_16x16x32_bf16 v[30:33], v[180:183], v[196:199], v[30:33]
	v_mfma_f32_16x16x32_bf16 v[22:25], v[172:175], v[204:207], v[22:25]
	v_mfma_f32_16x16x32_bf16 v[14:17], v[180:183], v[204:207], v[14:17]
	v_mfma_f32_16x16x32_bf16 v[6:9], v[172:175], v[212:215], v[6:9]
	v_mfma_f32_16x16x32_bf16 v[2:5], v[180:183], v[212:215], v[2:5]
	v_mfma_f32_16x16x32_bf16 v[54:57], v[176:179], v[192:195], v[54:57]
	v_mfma_f32_16x16x32_bf16 v[50:53], v[184:187], v[192:195], v[50:53]
	v_mfma_f32_16x16x32_bf16 v[38:41], v[176:179], v[200:203], v[38:41]
	v_mfma_f32_16x16x32_bf16 v[30:33], v[184:187], v[200:203], v[30:33]
	v_mfma_f32_16x16x32_bf16 v[22:25], v[176:179], v[208:211], v[22:25]
	v_mfma_f32_16x16x32_bf16 v[14:17], v[184:187], v[208:211], v[14:17]
	v_mfma_f32_16x16x32_bf16 v[6:9], v[176:179], v[220:223], v[6:9]
	v_mfma_f32_16x16x32_bf16 v[2:5], v[184:187], v[220:223], v[2:5]
	s_barrier
	s_setprio 0
	s_add_i32 s75, s75, 2
	s_add_u32 s24, s24, 0x10000
	s_addc_u32 s25, s25, 0
	s_add_u32 s73, s73, 0x10000
	s_addc_u32 s74, s74, 0
	s_cmp_gt_u32 s75, 13
	s_cbranch_scc0 .LBB0_150
	s_and_b64 vcc, exec, s[12:13]
	s_cbranch_vccz .LBB0_153
	s_barrier

; #define PG8_STAGE(bufoff, gbase, voff) do { _Pragma("unroll") for (int _i = 0; _i < 2; ++_i) \
;         __builtin_amdgcn_global_load_lds((const unsigned*)((const char*)(gbase) + (voff)[_i]), (PG8_LAS unsigned*)(lds + (bufoff) + ldsw + _i * 8192), 16, 0, 0); } while (0)
; #define PG8_LDA(dst, b, h) do { _Pragma("unroll") for (int m = 0; m < 4; ++m) _Pragma("unroll") for (int k = 0; k < 2; ++k) dst[m][k] = *(const PG8_LAS bf16x8*)(lds + PG8_SA(b, h) + aoff + m * 2048 + k * 1024); } while (0)
; #define PG8_LDB(dst, b, h) do { _Pragma("unroll") for (int n = 0; n < 2; ++n) _Pragma("unroll") for (int k = 0; k < 2; ++k) dst[n][k] = *(const PG8_LAS bf16x8*)(lds + PG8_SB(b, h) + boff + n * 2048 + k * 1024); } while (0)
; #define PG8_MMA(ai, bj, At, Bt) do { __builtin_amdgcn_s_setprio(1); _Pragma("unroll") for (int m = 0; m < 4; ++m) _Pragma("unroll") for (int n = 0; n < 2; ++n) _Pragma("unroll") for (int k = 0; k < 2; ++k) \
;         acc[ai][bj][m][n] = __builtin_amdgcn_mfma_f32_16x16x32_bf16(Bt[n][k], At[m][k], acc[ai][bj][m][n], 0, 0, 0); __builtin_amdgcn_s_setprio(0); } while (0)
; #define PG8_WAIT_V(n) asm volatile("s_waitcnt vmcnt(" #n ")" ::: "memory")
; #define PG8_WAIT_L(n) asm volatile("s_waitcnt lgkmcnt(" #n ")" ::: "memory")
; #define PG8_BAR __builtin_amdgcn_s_barrier()
; #define PG8_SCHED __builtin_amdgcn_sched_barrier(0)
; template <class Epi, class Sched, bool ALIGN_EPI = false, bool SP2 = false>
; __device__ __forceinline__ void gemm_phase(PG8_LAS unsigned char* lds, const Gemm g, const Sched& S, const Epi& E) {
;     ...
;             const char* a1 = cA + (size_t)(t + 1) * kstep;
;             const char* a2 = last ? nA : cA + (size_t)(t + 2) * kstep; const char* b2 = last ? nB : cB + (size_t)(t + 2) * kstep;
;             const char* a3 = a2 + kstep; const char* b3 = b2 + kstep;
;             if (last && has_next) S.a_ready(nxt);
;             if constexpr (SP2) {
;             PG8_LDB(B0, 0, 0); PG8_LDB(B1, 0, 1); PG8_SCHED; PG8_LDA(At, 0, 0); PG8_STAGE(PG8_SA(1, 1), a1 + hstep, voffA);
;             PG8_WAIT_V(8); PG8_WAIT_L(0); PG8_BAR; PG8_MMA(0, 0, At, B0); PG8_MMA(0, 1, At, B1); PG8_BAR; PG8_SCHED;
;             PG8_LDA(At, 0, 1); PG8_STAGE(PG8_SB(0, 0), b2, voffB); PG8_STAGE(PG8_SB(0, 1), b2 + hstepB, voffB); PG8_STAGE(PG8_SA(0, 0), a2, voffA);
.LBB0_380:
	s_add_u32 s48, s28, s46
	v_add_u32_e32 v3, s87, v221
	s_addc_u32 s49, s29, s47
	ds_read_b128 v[134:137], v3
	ds_read_b128 v[138:141], v3 offset:1024
	ds_read_b128 v[142:145], v3 offset:2048
	ds_read_b128 v[146:149], v3 offset:3072
	v_add_u32_e32 v3, s88, v221
	s_add_u32 s48, s48, 0x10000
	ds_read_b128 v[150:153], v3
	ds_read_b128 v[154:157], v3 offset:1024
	ds_read_b128 v[158:161], v3 offset:2048
	ds_read_b128 v[162:165], v3 offset:3072
	s_addc_u32 s49, s49, 0
	s_add_u32 s50, s27, s46
	s_addc_u32 s51, s45, s47
	s_cmp_eq_u32 s46, 0x70000
	s_cselect_b32 s70, s1, s48
	s_cselect_b32 s71, s0, s49
	s_cselect_b32 s50, s21, s50
	s_cselect_b32 s51, s19, s51
	s_add_u32 s48, s70, 0x8000
	s_addc_u32 s49, s71, 0
	v_lshl_add_u64 v[4:5], v[182:183], 0, s[46:47]
	s_add_i32 m0, s74, 0xc000
	ds_read_b128 v[166:169], v225
	ds_read_b128 v[170:173], v225 offset:1024
	ds_read_b128 v[174:177], v225 offset:2048
	ds_read_b128 v[178:181], v225 offset:3072
	ds_read_b128 v[186:189], v225 offset:4096
	ds_read_b128 v[190:193], v225 offset:5120
	ds_read_b128 v[194:197], v225 offset:6144
	ds_read_b128 v[228:231], v225 offset:7168
	global_load_lds_dwordx4 v[4:5], off
	v_lshl_add_u64 v[4:5], v[184:185], 0, s[46:47]
	s_add_i32 m0, s74, 0xe000
	s_nop 0
	global_load_lds_dwordx4 v[4:5], off
	s_waitcnt vmcnt(8)
	s_waitcnt lgkmcnt(0)
	s_setprio 1
	s_barrier
	v_mfma_f32_16x16x32_bf16 v[130:133], v[134:137], v[166:169], v[130:133]
	v_mfma_f32_16x16x32_bf16 v[126:129], v[142:145], v[166:169], v[126:129]
	v_mfma_f32_16x16x32_bf16 v[114:117], v[134:137], v[174:177], v[114:117]
	v_mfma_f32_16x16x32_bf16 v[110:113], v[142:145], v[174:177], v[110:113]
	v_mfma_f32_16x16x32_bf16 v[98:101], v[134:137], v[186:189], v[98:101]
	v_mfma_f32_16x16x32_bf16 v[94:97], v[142:145], v[186:189], v[94:97]
	v_mfma_f32_16x16x32_bf16 v[82:85], v[134:137], v[194:197], v[82:85]
	v_mfma_f32_16x16x32_bf16 v[78:81], v[142:145], v[194:197], v[78:81]
	v_mfma_f32_16x16x32_bf16 v[130:133], v[138:141], v[170:173], v[130:133]
	v_mfma_f32_16x16x32_bf16 v[126:129], v[146:149], v[170:173], v[126:129]
	v_mfma_f32_16x16x32_bf16 v[114:117], v[138:141], v[178:181], v[114:117]
	v_mfma_f32_16x16x32_bf16 v[110:113], v[146:149], v[178:181], v[110:113]
	v_mfma_f32_16x16x32_bf16 v[98:101], v[138:141], v[190:193], v[98:101]
	v_mfma_f32_16x16x32_bf16 v[94:97], v[146:149], v[190:193], v[94:97]
	v_mfma_f32_16x16x32_bf16 v[82:85], v[138:141], v[228:231], v[82:85]
	v_mfma_f32_16x16x32_bf16 v[78:81], v[146:149], v[228:231], v[78:81]
	s_setprio 0
	s_setprio 1
	v_mfma_f32_16x16x32_bf16 v[122:125], v[150:153], v[166:169], v[122:125]
	v_mfma_f32_16x16x32_bf16 v[118:121], v[158:161], v[166:169], v[118:121]
	v_mfma_f32_16x16x32_bf16 v[106:109], v[150:153], v[174:177], v[106:109]
	v_mfma_f32_16x16x32_bf16 v[102:105], v[158:161], v[174:177], v[102:105]
	v_mfma_f32_16x16x32_bf16 v[90:93], v[150:153], v[186:189], v[90:93]
	v_mfma_f32_16x16x32_bf16 v[86:89], v[158:161], v[186:189], v[86:89]
	v_mfma_f32_16x16x32_bf16 v[74:77], v[150:153], v[194:197], v[74:77]
	v_mfma_f32_16x16x32_bf16 v[70:73], v[158:161], v[194:197], v[70:73]
	v_mfma_f32_16x16x32_bf16 v[122:125], v[154:157], v[170:173], v[122:125]
	v_mfma_f32_16x16x32_bf16 v[118:121], v[162:165], v[170:173], v[118:121]
	v_mfma_f32_16x16x32_bf16 v[106:109], v[154:157], v[178:181], v[106:109]
	v_mfma_f32_16x16x32_bf16 v[102:105], v[162:165], v[178:181], v[102:105]
	v_mfma_f32_16x16x32_bf16 v[90:93], v[154:157], v[190:193], v[90:93]
	v_mfma_f32_16x16x32_bf16 v[86:89], v[162:165], v[190:193], v[86:89]
	v_mfma_f32_16x16x32_bf16 v[74:77], v[154:157], v[228:231], v[74:77]
	v_mfma_f32_16x16x32_bf16 v[70:73], v[162:165], v[228:231], v[70:73]
	s_barrier
	s_setprio 0
	s_add_i32 s52, s87, s73
	v_lshl_add_u64 v[4:5], s[50:51], 0, v[200:201]
	s_mov_b32 m0, s52
	ds_read_b128 v[166:169], v225 offset:16384
	ds_read_b128 v[170:173], v225 offset:17408
	ds_read_b128 v[174:177], v225 offset:18432
	ds_read_b128 v[178:181], v225 offset:19456
	ds_read_b128 v[186:189], v225 offset:20480
	ds_read_b128 v[190:193], v225 offset:21504
	ds_read_b128 v[194:197], v225 offset:22528
	ds_read_b128 v[228:231], v225 offset:23552
	global_load_lds_dwordx4 v[4:5], off
	s_add_i32 m0, s52, 0x2000
	s_add_u32 s52, s50, 0x1000
	v_lshl_add_u64 v[4:5], s[50:51], 0, v[204:205]
	s_addc_u32 s53, s51, 0
	s_add_i32 s54, s88, s73
	global_load_lds_dwordx4 v[4:5], off
	v_lshl_add_u64 v[4:5], s[52:53], 0, v[200:201]
	s_mov_b32 m0, s54
	s_nop 0
	global_load_lds_dwordx4 v[4:5], off
	v_lshl_add_u64 v[4:5], s[52:53], 0, v[204:205]
	s_add_i32 m0, s54, 0x2000
	s_nop 0
	global_load_lds_dwordx4 v[4:5], off
	v_lshl_add_u64 v[4:5], s[70:71], 0, v[198:199]
	s_mov_b32 m0, s74
	s_nop 0
	global_load_lds_dwordx4 v[4:5], off
	v_lshl_add_u64 v[4:5], s[70:71], 0, v[202:203]
	s_mov_b32 m0, s75
	s_nop 0
	global_load_lds_dwordx4 v[4:5], off
	s_waitcnt vmcnt(8)
	s_waitcnt lgkmcnt(0)
	s_setprio 1
	s_barrier
; #define PG8_STAGE(bufoff, gbase, voff) do { _Pragma("unroll") for (int _i = 0; _i < 2; ++_i) \
;         __builtin_amdgcn_global_load_lds((const unsigned*)((const char*)(gbase) + (voff)[_i]), (PG8_LAS unsigned*)(lds + (bufoff) + ldsw + _i * 8192), 16, 0, 0); } while (0)
; #define PG8_LDA(dst, b, h) do { _Pragma("unroll") for (int m = 0; m < 4; ++m) _Pragma("unroll") for (int k = 0; k < 2; ++k) dst[m][k] = *(const PG8_LAS bf16x8*)(lds + PG8_SA(b, h) + aoff + m * 2048 + k * 1024); } while (0)
; #define PG8_LDB(dst, b, h) do { _Pragma("unroll") for (int n = 0; n < 2; ++n) _Pragma("unroll") for (int k = 0; k < 2; ++k) dst[n][k] = *(const PG8_LAS bf16x8*)(lds + PG8_SB(b, h) + boff + n * 2048 + k * 1024); } while (0)
; #define PG8_MMA(ai, bj, At, Bt) do { __builtin_amdgcn_s_setprio(1); _Pragma("unroll") for (int m = 0; m < 4; ++m) _Pragma("unroll") for (int n = 0; n < 2; ++n) _Pragma("unroll") for (int k = 0; k < 2; ++k) \
;         acc[ai][bj][m][n] = __builtin_amdgcn_mfma_f32_16x16x32_bf16(Bt[n][k], At[m][k], acc[ai][bj][m][n], 0, 0, 0); __builtin_amdgcn_s_setprio(0); } while (0)
; #define PG8_WAIT_V(n) asm volatile("s_waitcnt vmcnt(" #n ")" ::: "memory")
; #define PG8_WAIT_L(n) asm volatile("s_waitcnt lgkmcnt(" #n ")" ::: "memory")
; #define PG8_BAR __builtin_amdgcn_s_barrier()
; #define PG8_SCHED __builtin_amdgcn_sched_barrier(0)
; template <class Epi, class Sched, bool ALIGN_EPI = false, bool SP2 = false>
; __device__ __forceinline__ void gemm_phase(PG8_LAS unsigned char* lds, const Gemm g, const Sched& S, const Epi& E) {
;     ...
;             PG8_WAIT_V(8); PG8_WAIT_L(0); PG8_BAR; PG8_MMA(1, 0, At, B0); PG8_MMA(1, 1, At, B1); PG8_BAR; PG8_SCHED;
;             PG8_LDB(B0, 1, 0); PG8_LDB(B1, 1, 1); PG8_SCHED; PG8_LDA(At, 1, 0); PG8_STAGE(PG8_SA(0, 1), a2 + hstep, voffA);
;             PG8_WAIT_V(8); PG8_WAIT_L(0); PG8_BAR; PG8_MMA(0, 0, At, B0); PG8_MMA(0, 1, At, B1); PG8_BAR; PG8_SCHED;
	v_mfma_f32_16x16x32_bf16 v[66:69], v[134:137], v[166:169], v[66:69]
	v_mfma_f32_16x16x32_bf16 v[62:65], v[142:145], v[166:169], v[62:65]
	v_mfma_f32_16x16x32_bf16 v[50:53], v[134:137], v[174:177], v[50:53]
	v_mfma_f32_16x16x32_bf16 v[46:49], v[142:145], v[174:177], v[46:49]
	v_mfma_f32_16x16x32_bf16 v[34:37], v[134:137], v[186:189], v[34:37]
	v_mfma_f32_16x16x32_bf16 v[30:33], v[142:145], v[186:189], v[30:33]
	v_mfma_f32_16x16x32_bf16 v[18:21], v[134:137], v[194:197], v[18:21]
	v_mfma_f32_16x16x32_bf16 v[14:17], v[142:145], v[194:197], v[14:17]
	v_mfma_f32_16x16x32_bf16 v[66:69], v[138:141], v[170:173], v[66:69]
	v_mfma_f32_16x16x32_bf16 v[62:65], v[146:149], v[170:173], v[62:65]
	v_mfma_f32_16x16x32_bf16 v[50:53], v[138:141], v[178:181], v[50:53]
	v_mfma_f32_16x16x32_bf16 v[46:49], v[146:149], v[178:181], v[46:49]
	v_mfma_f32_16x16x32_bf16 v[34:37], v[138:141], v[190:193], v[34:37]
	v_mfma_f32_16x16x32_bf16 v[30:33], v[146:149], v[190:193], v[30:33]
	v_mfma_f32_16x16x32_bf16 v[18:21], v[138:141], v[228:231], v[18:21]
	v_mfma_f32_16x16x32_bf16 v[14:17], v[146:149], v[228:231], v[14:17]
	s_setprio 0
	s_setprio 1
	v_mfma_f32_16x16x32_bf16 v[58:61], v[150:153], v[166:169], v[58:61]
	v_mfma_f32_16x16x32_bf16 v[54:57], v[158:161], v[166:169], v[54:57]
	v_mfma_f32_16x16x32_bf16 v[42:45], v[150:153], v[174:177], v[42:45]
	v_mfma_f32_16x16x32_bf16 v[38:41], v[158:161], v[174:177], v[38:41]
	v_mfma_f32_16x16x32_bf16 v[26:29], v[150:153], v[186:189], v[26:29]
	v_mfma_f32_16x16x32_bf16 v[22:25], v[158:161], v[186:189], v[22:25]
	v_mfma_f32_16x16x32_bf16 v[10:13], v[150:153], v[194:197], v[10:13]
	v_mfma_f32_16x16x32_bf16 v[4:7], v[158:161], v[194:197], v[6:9]
	v_mfma_f32_16x16x32_bf16 v[58:61], v[154:157], v[170:173], v[58:61]
	v_mfma_f32_16x16x32_bf16 v[54:57], v[162:165], v[170:173], v[54:57]
	v_mfma_f32_16x16x32_bf16 v[42:45], v[154:157], v[178:181], v[42:45]
	v_mfma_f32_16x16x32_bf16 v[38:41], v[162:165], v[178:181], v[38:41]
	v_mfma_f32_16x16x32_bf16 v[26:29], v[154:157], v[190:193], v[26:29]
	v_mfma_f32_16x16x32_bf16 v[22:25], v[162:165], v[190:193], v[22:25]
	v_mfma_f32_16x16x32_bf16 v[10:13], v[154:157], v[228:231], v[10:13]
	v_mfma_f32_16x16x32_bf16 v[4:7], v[162:165], v[228:231], v[4:7]
	s_barrier
	s_setprio 0
	s_add_i32 s54, 0, 0x18000
	v_add_u32_e32 v3, s54, v221
	s_add_i32 s55, 0, 0x1c000
	ds_read_b128 v[134:137], v3
	ds_read_b128 v[138:141], v3 offset:1024
	ds_read_b128 v[142:145], v3 offset:2048
	ds_read_b128 v[146:149], v3 offset:3072
	v_add_u32_e32 v3, s55, v221
	ds_read_b128 v[150:153], v3
	ds_read_b128 v[154:157], v3 offset:1024
	ds_read_b128 v[158:161], v3 offset:2048
	ds_read_b128 v[162:165], v3 offset:3072
	s_add_u32 s52, s70, 0x4000
	s_addc_u32 s53, s71, 0
	s_mov_b32 m0, s77
	v_lshl_add_u64 v[8:9], s[52:53], 0, v[198:199]
	ds_read_b128 v[166:169], v225 offset:32768
	ds_read_b128 v[170:173], v225 offset:33792
	ds_read_b128 v[174:177], v225 offset:34816
	ds_read_b128 v[178:181], v225 offset:35840
	ds_read_b128 v[186:189], v225 offset:36864
	ds_read_b128 v[190:193], v225 offset:37888
	ds_read_b128 v[194:197], v225 offset:38912
	ds_read_b128 v[228:231], v225 offset:39936
	global_load_lds_dwordx4 v[8:9], off
	v_lshl_add_u64 v[8:9], s[52:53], 0, v[202:203]
	s_mov_b32 m0, s78
	s_nop 0
	global_load_lds_dwordx4 v[8:9], off
	s_waitcnt vmcnt(8)
	s_waitcnt lgkmcnt(0)
	s_setprio 1
	s_barrier
	v_mfma_f32_16x16x32_bf16 v[130:133], v[134:137], v[166:169], v[130:133]
	v_mfma_f32_16x16x32_bf16 v[126:129], v[142:145], v[166:169], v[126:129]
	v_mfma_f32_16x16x32_bf16 v[114:117], v[134:137], v[174:177], v[114:117]
	v_mfma_f32_16x16x32_bf16 v[110:113], v[142:145], v[174:177], v[110:113]
	v_mfma_f32_16x16x32_bf16 v[98:101], v[134:137], v[186:189], v[98:101]
	v_mfma_f32_16x16x32_bf16 v[94:97], v[142:145], v[186:189], v[94:97]
	v_mfma_f32_16x16x32_bf16 v[82:85], v[134:137], v[194:197], v[82:85]
	v_mfma_f32_16x16x32_bf16 v[78:81], v[142:145], v[194:197], v[78:81]
	v_mfma_f32_16x16x32_bf16 v[130:133], v[138:141], v[170:173], v[130:133]
	v_mfma_f32_16x16x32_bf16 v[126:129], v[146:149], v[170:173], v[126:129]
	v_mfma_f32_16x16x32_bf16 v[114:117], v[138:141], v[178:181], v[114:117]
	v_mfma_f32_16x16x32_bf16 v[110:113], v[146:149], v[178:181], v[110:113]
	v_mfma_f32_16x16x32_bf16 v[98:101], v[138:141], v[190:193], v[98:101]
	v_mfma_f32_16x16x32_bf16 v[94:97], v[146:149], v[190:193], v[94:97]
	v_mfma_f32_16x16x32_bf16 v[82:85], v[138:141], v[228:231], v[82:85]
	v_mfma_f32_16x16x32_bf16 v[78:81], v[146:149], v[228:231], v[78:81]
	s_setprio 0
	s_setprio 1
	v_mfma_f32_16x16x32_bf16 v[122:125], v[150:153], v[166:169], v[122:125]
	v_mfma_f32_16x16x32_bf16 v[118:121], v[158:161], v[166:169], v[118:121]
	v_mfma_f32_16x16x32_bf16 v[106:109], v[150:153], v[174:177], v[106:109]
	v_mfma_f32_16x16x32_bf16 v[102:105], v[158:161], v[174:177], v[102:105]
	v_mfma_f32_16x16x32_bf16 v[90:93], v[150:153], v[186:189], v[90:93]
	v_mfma_f32_16x16x32_bf16 v[86:89], v[158:161], v[186:189], v[86:89]
	v_mfma_f32_16x16x32_bf16 v[74:77], v[150:153], v[194:197], v[74:77]
	v_mfma_f32_16x16x32_bf16 v[70:73], v[158:161], v[194:197], v[70:73]
	v_mfma_f32_16x16x32_bf16 v[122:125], v[154:157], v[170:173], v[122:125]
	v_mfma_f32_16x16x32_bf16 v[118:121], v[162:165], v[170:173], v[118:121]
	v_mfma_f32_16x16x32_bf16 v[106:109], v[154:157], v[178:181], v[106:109]
	v_mfma_f32_16x16x32_bf16 v[102:105], v[162:165], v[178:181], v[102:105]
	v_mfma_f32_16x16x32_bf16 v[90:93], v[154:157], v[190:193], v[90:93]
	v_mfma_f32_16x16x32_bf16 v[86:89], v[162:165], v[190:193], v[86:89]
	v_mfma_f32_16x16x32_bf16 v[74:77], v[154:157], v[228:231], v[74:77]
	v_mfma_f32_16x16x32_bf16 v[70:73], v[162:165], v[228:231], v[70:73]
	s_barrier
; #define PG8_STAGE(bufoff, gbase, voff) do { _Pragma("unroll") for (int _i = 0; _i < 2; ++_i) \
;         __builtin_amdgcn_global_load_lds((const unsigned*)((const char*)(gbase) + (voff)[_i]), (PG8_LAS unsigned*)(lds + (bufoff) + ldsw + _i * 8192), 16, 0, 0); } while (0)
; #define PG8_LDA(dst, b, h) do { _Pragma("unroll") for (int m = 0; m < 4; ++m) _Pragma("unroll") for (int k = 0; k < 2; ++k) dst[m][k] = *(const PG8_LAS bf16x8*)(lds + PG8_SA(b, h) + aoff + m * 2048 + k * 1024); } while (0)
; #define PG8_MMA(ai, bj, At, Bt) do { __builtin_amdgcn_s_setprio(1); _Pragma("unroll") for (int m = 0; m < 4; ++m) _Pragma("unroll") for (int n = 0; n < 2; ++n) _Pragma("unroll") for (int k = 0; k < 2; ++k) \
;         acc[ai][bj][m][n] = __builtin_amdgcn_mfma_f32_16x16x32_bf16(Bt[n][k], At[m][k], acc[ai][bj][m][n], 0, 0, 0); __builtin_amdgcn_s_setprio(0); } while (0)
; #define PG8_WAIT_V(n) asm volatile("s_waitcnt vmcnt(" #n ")" ::: "memory")
; #define PG8_WAIT_L(n) asm volatile("s_waitcnt lgkmcnt(" #n ")" ::: "memory")
; #define PG8_BAR __builtin_amdgcn_s_barrier()
; #define PG8_SCHED __builtin_amdgcn_sched_barrier(0)
; template <class Epi, class Sched, bool ALIGN_EPI = false, bool SP2 = false>
; __device__ __forceinline__ void gemm_phase(PG8_LAS unsigned char* lds, const Gemm g, const Sched& S, const Epi& E) {
;     ...
;             PG8_LDA(At, 1, 1); PG8_STAGE(PG8_SB(1, 0), b3, voffB); PG8_STAGE(PG8_SB(1, 1), b3 + hstepB, voffB); PG8_STAGE(PG8_SA(1, 0), a3, voffA);
;             PG8_WAIT_V(8); PG8_WAIT_L(0); PG8_BAR; PG8_MMA(1, 0, At, B0); PG8_MMA(1, 1, At, B1); PG8_BAR; PG8_SCHED;
	s_setprio 0
	s_add_u32 s52, s50, 0x8000
	s_addc_u32 s53, s51, 0
	s_add_i32 s54, s54, s73
	v_lshl_add_u64 v[8:9], s[52:53], 0, v[200:201]
	s_mov_b32 m0, s54
	ds_read_b128 v[166:169], v225 offset:49152
	ds_read_b128 v[170:173], v225 offset:50176
	ds_read_b128 v[174:177], v225 offset:51200
	ds_read_b128 v[178:181], v225 offset:52224
	ds_read_b128 v[186:189], v225 offset:53248
	ds_read_b128 v[190:193], v225 offset:54272
	ds_read_b128 v[194:197], v225 offset:55296
	ds_read_b128 v[228:231], v225 offset:56320
	global_load_lds_dwordx4 v[8:9], off
	s_add_i32 m0, s54, 0x2000
	s_add_u32 s50, s50, 0x9000
	v_lshl_add_u64 v[8:9], s[52:53], 0, v[204:205]
	s_addc_u32 s51, s51, 0
	s_add_i32 s52, s55, s73
	global_load_lds_dwordx4 v[8:9], off
	v_lshl_add_u64 v[8:9], s[50:51], 0, v[200:201]
	s_mov_b32 m0, s52
	s_nop 0
	global_load_lds_dwordx4 v[8:9], off
	v_lshl_add_u64 v[8:9], s[50:51], 0, v[204:205]
	s_add_i32 m0, s52, 0x2000
	s_nop 0
	global_load_lds_dwordx4 v[8:9], off
	v_lshl_add_u64 v[8:9], s[48:49], 0, v[198:199]
	s_mov_b32 m0, s81
	s_nop 0
	global_load_lds_dwordx4 v[8:9], off
	v_lshl_add_u64 v[8:9], s[48:49], 0, v[202:203]
	s_mov_b32 m0, s82
	s_nop 0
	global_load_lds_dwordx4 v[8:9], off
	s_waitcnt vmcnt(8)
	s_waitcnt lgkmcnt(0)
	s_setprio 1
	s_barrier
	v_mfma_f32_16x16x32_bf16 v[66:69], v[134:137], v[166:169], v[66:69]
	v_mfma_f32_16x16x32_bf16 v[62:65], v[142:145], v[166:169], v[62:65]
	v_mfma_f32_16x16x32_bf16 v[50:53], v[134:137], v[174:177], v[50:53]
	v_mfma_f32_16x16x32_bf16 v[46:49], v[142:145], v[174:177], v[46:49]
	v_mfma_f32_16x16x32_bf16 v[34:37], v[134:137], v[186:189], v[34:37]
	v_mfma_f32_16x16x32_bf16 v[30:33], v[142:145], v[186:189], v[30:33]
	v_mfma_f32_16x16x32_bf16 v[18:21], v[134:137], v[194:197], v[18:21]
	v_mfma_f32_16x16x32_bf16 v[14:17], v[142:145], v[194:197], v[14:17]
	v_mfma_f32_16x16x32_bf16 v[66:69], v[138:141], v[170:173], v[66:69]
	v_mfma_f32_16x16x32_bf16 v[62:65], v[146:149], v[170:173], v[62:65]
	v_mfma_f32_16x16x32_bf16 v[50:53], v[138:141], v[178:181], v[50:53]
	v_mfma_f32_16x16x32_bf16 v[46:49], v[146:149], v[178:181], v[46:49]
	v_mfma_f32_16x16x32_bf16 v[34:37], v[138:141], v[190:193], v[34:37]
	v_mfma_f32_16x16x32_bf16 v[30:33], v[146:149], v[190:193], v[30:33]
	v_mfma_f32_16x16x32_bf16 v[18:21], v[138:141], v[228:231], v[18:21]
	v_mfma_f32_16x16x32_bf16 v[14:17], v[146:149], v[228:231], v[14:17]
	s_setprio 0
	s_setprio 1
	v_mfma_f32_16x16x32_bf16 v[58:61], v[150:153], v[166:169], v[58:61]
	v_mfma_f32_16x16x32_bf16 v[54:57], v[158:161], v[166:169], v[54:57]
	v_mfma_f32_16x16x32_bf16 v[42:45], v[150:153], v[174:177], v[42:45]
	v_mfma_f32_16x16x32_bf16 v[38:41], v[158:161], v[174:177], v[38:41]
	v_mfma_f32_16x16x32_bf16 v[26:29], v[150:153], v[186:189], v[26:29]
	v_mfma_f32_16x16x32_bf16 v[22:25], v[158:161], v[186:189], v[22:25]
	v_mfma_f32_16x16x32_bf16 v[8:11], v[150:153], v[194:197], v[10:13]
	v_mfma_f32_16x16x32_bf16 v[4:7], v[158:161], v[194:197], v[4:7]
	v_mfma_f32_16x16x32_bf16 v[58:61], v[154:157], v[170:173], v[58:61]
	v_mfma_f32_16x16x32_bf16 v[54:57], v[162:165], v[170:173], v[54:57]
	v_mfma_f32_16x16x32_bf16 v[42:45], v[154:157], v[178:181], v[42:45]
	v_mfma_f32_16x16x32_bf16 v[38:41], v[162:165], v[178:181], v[38:41]
	v_mfma_f32_16x16x32_bf16 v[26:29], v[154:157], v[190:193], v[26:29]
	v_mfma_f32_16x16x32_bf16 v[22:25], v[162:165], v[190:193], v[22:25]
	v_mfma_f32_16x16x32_bf16 v[10:13], v[154:157], v[228:231], v[8:11]
	v_mfma_f32_16x16x32_bf16 v[6:9], v[162:165], v[228:231], v[4:7]
	s_barrier
	s_setprio 0
	s_add_i32 s56, s56, 2
	s_add_u32 s46, s46, 0x10000
	s_addc_u32 s47, s47, 0
	s_cmp_gt_u32 s56, 13
	s_cbranch_scc1 .LBB0_383

; #define PG8_STAGE(bufoff, gbase, voff) do { _Pragma("unroll") for (int _i = 0; _i < 2; ++_i) \
;         __builtin_amdgcn_global_load_lds((const unsigned*)((const char*)(gbase) + (voff)[_i]), (PG8_LAS unsigned*)(lds + (bufoff) + ldsw + _i * 8192), 16, 0, 0); } while (0)
; #define PG8_LDA(dst, b, h) do { _Pragma("unroll") for (int m = 0; m < 4; ++m) _Pragma("unroll") for (int k = 0; k < 2; ++k) dst[m][k] = *(const PG8_LAS bf16x8*)(lds + PG8_SA(b, h) + aoff + m * 2048 + k * 1024); } while (0)
; #define PG8_LDB(dst, b, h) do { _Pragma("unroll") for (int n = 0; n < 2; ++n) _Pragma("unroll") for (int k = 0; k < 2; ++k) dst[n][k] = *(const PG8_LAS bf16x8*)(lds + PG8_SB(b, h) + boff + n * 2048 + k * 1024); } while (0)
; #define PG8_MMA(ai, bj, At, Bt) do { __builtin_amdgcn_s_setprio(1); _Pragma("unroll") for (int m = 0; m < 4; ++m) _Pragma("unroll") for (int n = 0; n < 2; ++n) _Pragma("unroll") for (int k = 0; k < 2; ++k) \
;         acc[ai][bj][m][n] = __builtin_amdgcn_mfma_f32_16x16x32_bf16(Bt[n][k], At[m][k], acc[ai][bj][m][n], 0, 0, 0); __builtin_amdgcn_s_setprio(0); } while (0)
; #define PG8_WAIT_V(n) asm volatile("s_waitcnt vmcnt(" #n ")" ::: "memory")
; #define PG8_WAIT_L(n) asm volatile("s_waitcnt lgkmcnt(" #n ")" ::: "memory")
; #define PG8_BAR __builtin_amdgcn_s_barrier()
; #define PG8_SCHED __builtin_amdgcn_sched_barrier(0)
; template <class Epi, class Sched, bool ALIGN_EPI = false, bool SP2 = false>
; __device__ __forceinline__ void gemm_phase(PG8_LAS unsigned char* lds, const Gemm g, const Sched& S, const Epi& E) {
;     ...
;             PG8_LDB(B0, 0, 0); PG8_LDB(B1, 0, 1); PG8_SCHED; PG8_LDA(At, 0, 0); PG8_STAGE(PG8_SA(1, 1), a1 + hstep, voffA);
;             PG8_WAIT_V(8); PG8_WAIT_L(0); PG8_BAR; PG8_MMA(0, 0, At, B0); PG8_MMA(0, 1, At, B1); PG8_BAR; PG8_SCHED;
;             PG8_LDA(At, 0, 1); PG8_STAGE(PG8_SB(0, 0), b2, voffB); PG8_STAGE(PG8_SB(0, 1), b2 + hstepB, voffB); PG8_STAGE(PG8_SA(0, 0), a2, voffA);
.LBB0_477:
	ds_read_b128 v[130:133], v201
	ds_read_b128 v[134:137], v201 offset:1024
	ds_read_b128 v[138:141], v201 offset:2048
	ds_read_b128 v[142:145], v201 offset:3072
	ds_read_b128 v[146:149], v202
	ds_read_b128 v[150:153], v202 offset:1024
	ds_read_b128 v[154:157], v202 offset:2048
	ds_read_b128 v[158:161], v202 offset:3072
	s_add_u32 s68, s50, 0x4000
	s_addc_u32 s69, s51, 0
	s_cmp_eq_u32 s55, 12
	s_cselect_b32 s72, s47, s68
	s_cselect_b32 s73, s29, s69
	s_cselect_b32 s70, s52, s53
	s_cselect_b32 s71, s27, s54
	s_add_u32 s68, s72, 0x8000
	s_addc_u32 s69, s73, 0
	v_lshl_add_u64 v[196:197], s[50:51], 0, v[188:189]
	s_add_i32 m0, s1, 0xc000
	ds_read_b128 v[162:165], v203
	ds_read_b128 v[166:169], v203 offset:1024
	ds_read_b128 v[170:173], v203 offset:2048
	ds_read_b128 v[174:177], v203 offset:3072
	ds_read_b128 v[208:211], v203 offset:4096
	ds_read_b128 v[212:215], v203 offset:5120
	ds_read_b128 v[220:223], v203 offset:6144
	ds_read_b128 v[224:227], v203 offset:7168
	global_load_lds_dwordx4 v[196:197], off
	v_lshl_add_u64 v[196:197], s[50:51], 0, v[190:191]
	s_add_i32 m0, s1, 0xe000
	s_nop 0
	global_load_lds_dwordx4 v[196:197], off
	s_waitcnt vmcnt(8)
	s_waitcnt lgkmcnt(0)
	s_setprio 1
	s_barrier
	v_mfma_f32_16x16x32_bf16 v[126:129], v[130:133], v[162:165], v[126:129]
	v_mfma_f32_16x16x32_bf16 v[122:125], v[138:141], v[162:165], v[122:125]
	v_mfma_f32_16x16x32_bf16 v[110:113], v[130:133], v[170:173], v[110:113]
	v_mfma_f32_16x16x32_bf16 v[106:109], v[138:141], v[170:173], v[106:109]
	v_mfma_f32_16x16x32_bf16 v[94:97], v[130:133], v[208:211], v[94:97]
	v_mfma_f32_16x16x32_bf16 v[90:93], v[138:141], v[208:211], v[90:93]
	v_mfma_f32_16x16x32_bf16 v[78:81], v[130:133], v[220:223], v[78:81]
	v_mfma_f32_16x16x32_bf16 v[74:77], v[138:141], v[220:223], v[74:77]
	v_mfma_f32_16x16x32_bf16 v[126:129], v[134:137], v[166:169], v[126:129]
	v_mfma_f32_16x16x32_bf16 v[122:125], v[142:145], v[166:169], v[122:125]
	v_mfma_f32_16x16x32_bf16 v[110:113], v[134:137], v[174:177], v[110:113]
	v_mfma_f32_16x16x32_bf16 v[106:109], v[142:145], v[174:177], v[106:109]
	v_mfma_f32_16x16x32_bf16 v[94:97], v[134:137], v[212:215], v[94:97]
	v_mfma_f32_16x16x32_bf16 v[90:93], v[142:145], v[212:215], v[90:93]
	v_mfma_f32_16x16x32_bf16 v[78:81], v[134:137], v[224:227], v[78:81]
	v_mfma_f32_16x16x32_bf16 v[74:77], v[142:145], v[224:227], v[74:77]
	s_setprio 0
	s_setprio 1
	v_mfma_f32_16x16x32_bf16 v[118:121], v[146:149], v[162:165], v[118:121]
	v_mfma_f32_16x16x32_bf16 v[114:117], v[154:157], v[162:165], v[114:117]
	v_mfma_f32_16x16x32_bf16 v[102:105], v[146:149], v[170:173], v[102:105]
	v_mfma_f32_16x16x32_bf16 v[98:101], v[154:157], v[170:173], v[98:101]
	v_mfma_f32_16x16x32_bf16 v[86:89], v[146:149], v[208:211], v[86:89]
	v_mfma_f32_16x16x32_bf16 v[82:85], v[154:157], v[208:211], v[82:85]
	v_mfma_f32_16x16x32_bf16 v[70:73], v[146:149], v[220:223], v[70:73]
	v_mfma_f32_16x16x32_bf16 v[66:69], v[154:157], v[220:223], v[66:69]
	v_mfma_f32_16x16x32_bf16 v[118:121], v[150:153], v[166:169], v[118:121]
	v_mfma_f32_16x16x32_bf16 v[114:117], v[158:161], v[166:169], v[114:117]
	v_mfma_f32_16x16x32_bf16 v[102:105], v[150:153], v[174:177], v[102:105]
	v_mfma_f32_16x16x32_bf16 v[98:101], v[158:161], v[174:177], v[98:101]
	v_mfma_f32_16x16x32_bf16 v[86:89], v[150:153], v[212:215], v[86:89]
	v_mfma_f32_16x16x32_bf16 v[82:85], v[158:161], v[212:215], v[82:85]
	v_mfma_f32_16x16x32_bf16 v[70:73], v[150:153], v[224:227], v[70:73]
	v_mfma_f32_16x16x32_bf16 v[66:69], v[158:161], v[224:227], v[66:69]
	s_barrier
	s_setprio 0
	s_add_i32 s79, s77, s0
	v_lshl_add_u64 v[196:197], s[70:71], 0, v[180:181]
	s_mov_b32 m0, s79
	ds_read_b128 v[162:165], v203 offset:16384
	ds_read_b128 v[166:169], v203 offset:17408
	ds_read_b128 v[170:173], v203 offset:18432
	ds_read_b128 v[174:177], v203 offset:19456
	ds_read_b128 v[208:211], v203 offset:20480
	ds_read_b128 v[212:215], v203 offset:21504
	ds_read_b128 v[220:223], v203 offset:22528
	ds_read_b128 v[224:227], v203 offset:23552
	global_load_lds_dwordx4 v[196:197], off
	s_add_i32 m0, s79, 0x2000
	s_add_u32 s80, s70, 0x1000
	v_lshl_add_u64 v[196:197], s[70:71], 0, v[184:185]
	s_addc_u32 s81, s71, 0
	s_add_i32 s79, s78, s0
	global_load_lds_dwordx4 v[196:197], off
	v_lshl_add_u64 v[196:197], s[80:81], 0, v[180:181]
	s_mov_b32 m0, s79
	s_nop 0
	global_load_lds_dwordx4 v[196:197], off
	v_lshl_add_u64 v[196:197], s[80:81], 0, v[184:185]
	s_add_i32 m0, s79, 0x2000
	s_nop 0
	global_load_lds_dwordx4 v[196:197], off
	v_lshl_add_u64 v[196:197], s[72:73], 0, v[178:179]
	s_mov_b32 m0, s1
	s_nop 0
	global_load_lds_dwordx4 v[196:197], off
	v_lshl_add_u64 v[196:197], s[72:73], 0, v[182:183]
	s_mov_b32 m0, s49
	s_nop 0
	global_load_lds_dwordx4 v[196:197], off
	s_waitcnt vmcnt(8)
	s_waitcnt lgkmcnt(0)
	s_setprio 1
	s_barrier
; #define PG8_STAGE(bufoff, gbase, voff) do { _Pragma("unroll") for (int _i = 0; _i < 2; ++_i) \
;         __builtin_amdgcn_global_load_lds((const unsigned*)((const char*)(gbase) + (voff)[_i]), (PG8_LAS unsigned*)(lds + (bufoff) + ldsw + _i * 8192), 16, 0, 0); } while (0)
; #define PG8_LDA(dst, b, h) do { _Pragma("unroll") for (int m = 0; m < 4; ++m) _Pragma("unroll") for (int k = 0; k < 2; ++k) dst[m][k] = *(const PG8_LAS bf16x8*)(lds + PG8_SA(b, h) + aoff + m * 2048 + k * 1024); } while (0)
; #define PG8_LDB(dst, b, h) do { _Pragma("unroll") for (int n = 0; n < 2; ++n) _Pragma("unroll") for (int k = 0; k < 2; ++k) dst[n][k] = *(const PG8_LAS bf16x8*)(lds + PG8_SB(b, h) + boff + n * 2048 + k * 1024); } while (0)
; #define PG8_MMA(ai, bj, At, Bt) do { __builtin_amdgcn_s_setprio(1); _Pragma("unroll") for (int m = 0; m < 4; ++m) _Pragma("unroll") for (int n = 0; n < 2; ++n) _Pragma("unroll") for (int k = 0; k < 2; ++k) \
;         acc[ai][bj][m][n] = __builtin_amdgcn_mfma_f32_16x16x32_bf16(Bt[n][k], At[m][k], acc[ai][bj][m][n], 0, 0, 0); __builtin_amdgcn_s_setprio(0); } while (0)
; #define PG8_WAIT_V(n) asm volatile("s_waitcnt vmcnt(" #n ")" ::: "memory")
; #define PG8_WAIT_L(n) asm volatile("s_waitcnt lgkmcnt(" #n ")" ::: "memory")
; #define PG8_BAR __builtin_amdgcn_s_barrier()
; #define PG8_SCHED __builtin_amdgcn_sched_barrier(0)
; template <class Epi, class Sched, bool ALIGN_EPI = false, bool SP2 = false>
; __device__ __forceinline__ void gemm_phase(PG8_LAS unsigned char* lds, const Gemm g, const Sched& S, const Epi& E) {
;     ...
;             PG8_WAIT_V(8); PG8_WAIT_L(0); PG8_BAR; PG8_MMA(1, 0, At, B0); PG8_MMA(1, 1, At, B1); PG8_BAR; PG8_SCHED;
;             PG8_LDB(B0, 1, 0); PG8_LDB(B1, 1, 1); PG8_SCHED; PG8_LDA(At, 1, 0); PG8_STAGE(PG8_SA(0, 1), a2 + hstep, voffA);
;             PG8_WAIT_V(8); PG8_WAIT_L(0); PG8_BAR; PG8_MMA(0, 0, At, B0); PG8_MMA(0, 1, At, B1); PG8_BAR; PG8_SCHED;
	v_mfma_f32_16x16x32_bf16 v[62:65], v[130:133], v[162:165], v[62:65]
	v_mfma_f32_16x16x32_bf16 v[58:61], v[138:141], v[162:165], v[58:61]
	v_mfma_f32_16x16x32_bf16 v[46:49], v[130:133], v[170:173], v[46:49]
	v_mfma_f32_16x16x32_bf16 v[42:45], v[138:141], v[170:173], v[42:45]
	v_mfma_f32_16x16x32_bf16 v[30:33], v[130:133], v[208:211], v[30:33]
	v_mfma_f32_16x16x32_bf16 v[26:29], v[138:141], v[208:211], v[26:29]
	v_mfma_f32_16x16x32_bf16 v[14:17], v[130:133], v[220:223], v[14:17]
	v_mfma_f32_16x16x32_bf16 v[10:13], v[138:141], v[220:223], v[10:13]
	v_mfma_f32_16x16x32_bf16 v[62:65], v[134:137], v[166:169], v[62:65]
	v_mfma_f32_16x16x32_bf16 v[58:61], v[142:145], v[166:169], v[58:61]
	v_mfma_f32_16x16x32_bf16 v[46:49], v[134:137], v[174:177], v[46:49]
	v_mfma_f32_16x16x32_bf16 v[42:45], v[142:145], v[174:177], v[42:45]
	v_mfma_f32_16x16x32_bf16 v[30:33], v[134:137], v[212:215], v[30:33]
	v_mfma_f32_16x16x32_bf16 v[26:29], v[142:145], v[212:215], v[26:29]
	v_mfma_f32_16x16x32_bf16 v[14:17], v[134:137], v[224:227], v[14:17]
	v_mfma_f32_16x16x32_bf16 v[10:13], v[142:145], v[224:227], v[10:13]
	s_setprio 0
	s_setprio 1
	v_mfma_f32_16x16x32_bf16 v[54:57], v[146:149], v[162:165], v[54:57]
	v_mfma_f32_16x16x32_bf16 v[50:53], v[154:157], v[162:165], v[50:53]
	v_mfma_f32_16x16x32_bf16 v[38:41], v[146:149], v[170:173], v[38:41]
	v_mfma_f32_16x16x32_bf16 v[34:37], v[154:157], v[170:173], v[34:37]
	v_mfma_f32_16x16x32_bf16 v[22:25], v[146:149], v[208:211], v[22:25]
	v_mfma_f32_16x16x32_bf16 v[18:21], v[154:157], v[208:211], v[18:21]
	v_mfma_f32_16x16x32_bf16 v[6:9], v[146:149], v[220:223], v[6:9]
	v_mfma_f32_16x16x32_bf16 v[2:5], v[154:157], v[220:223], v[2:5]
	v_mfma_f32_16x16x32_bf16 v[54:57], v[150:153], v[166:169], v[54:57]
	v_mfma_f32_16x16x32_bf16 v[50:53], v[158:161], v[166:169], v[50:53]
	v_mfma_f32_16x16x32_bf16 v[38:41], v[150:153], v[174:177], v[38:41]
	v_mfma_f32_16x16x32_bf16 v[34:37], v[158:161], v[174:177], v[34:37]
	v_mfma_f32_16x16x32_bf16 v[22:25], v[150:153], v[212:215], v[22:25]
	v_mfma_f32_16x16x32_bf16 v[18:21], v[158:161], v[212:215], v[18:21]
	v_mfma_f32_16x16x32_bf16 v[6:9], v[150:153], v[224:227], v[6:9]
	v_mfma_f32_16x16x32_bf16 v[2:5], v[158:161], v[224:227], v[2:5]
	s_barrier
	s_setprio 0
	s_add_i32 s79, 0, 0x18000
	s_add_i32 s80, 0, 0x1c000
	v_add_u32_e32 v142, s79, v199
	v_add_u32_e32 v158, s80, v199
	ds_read_b128 v[130:133], v142
	ds_read_b128 v[134:137], v142 offset:1024
	ds_read_b128 v[138:141], v142 offset:2048
	ds_read_b128 v[142:145], v142 offset:3072
	ds_read_b128 v[146:149], v158
	ds_read_b128 v[150:153], v158 offset:1024
	ds_read_b128 v[154:157], v158 offset:2048
	ds_read_b128 v[158:161], v158 offset:3072
	s_add_u32 s72, s72, 0x4000
	s_addc_u32 s73, s73, 0
	s_mov_b32 m0, s56
	v_lshl_add_u64 v[196:197], s[72:73], 0, v[178:179]
	ds_read_b128 v[162:165], v203 offset:32768
	ds_read_b128 v[166:169], v203 offset:33792
	ds_read_b128 v[170:173], v203 offset:34816
	ds_read_b128 v[174:177], v203 offset:35840
	ds_read_b128 v[208:211], v203 offset:36864
	ds_read_b128 v[212:215], v203 offset:37888
	ds_read_b128 v[220:223], v203 offset:38912
	ds_read_b128 v[224:227], v203 offset:39936
	global_load_lds_dwordx4 v[196:197], off
	v_lshl_add_u64 v[196:197], s[72:73], 0, v[182:183]
	s_mov_b32 m0, s57
	s_nop 0
	global_load_lds_dwordx4 v[196:197], off
	s_waitcnt vmcnt(8)
	s_waitcnt lgkmcnt(0)
	s_setprio 1
	s_barrier
	v_mfma_f32_16x16x32_bf16 v[126:129], v[130:133], v[162:165], v[126:129]
	v_mfma_f32_16x16x32_bf16 v[122:125], v[138:141], v[162:165], v[122:125]
	v_mfma_f32_16x16x32_bf16 v[110:113], v[130:133], v[170:173], v[110:113]
	v_mfma_f32_16x16x32_bf16 v[106:109], v[138:141], v[170:173], v[106:109]
	v_mfma_f32_16x16x32_bf16 v[94:97], v[130:133], v[208:211], v[94:97]
	v_mfma_f32_16x16x32_bf16 v[90:93], v[138:141], v[208:211], v[90:93]
	v_mfma_f32_16x16x32_bf16 v[78:81], v[130:133], v[220:223], v[78:81]
	v_mfma_f32_16x16x32_bf16 v[74:77], v[138:141], v[220:223], v[74:77]
	v_mfma_f32_16x16x32_bf16 v[126:129], v[134:137], v[166:169], v[126:129]
	v_mfma_f32_16x16x32_bf16 v[122:125], v[142:145], v[166:169], v[122:125]
	v_mfma_f32_16x16x32_bf16 v[110:113], v[134:137], v[174:177], v[110:113]
	v_mfma_f32_16x16x32_bf16 v[106:109], v[142:145], v[174:177], v[106:109]
	v_mfma_f32_16x16x32_bf16 v[94:97], v[134:137], v[212:215], v[94:97]
	v_mfma_f32_16x16x32_bf16 v[90:93], v[142:145], v[212:215], v[90:93]
	v_mfma_f32_16x16x32_bf16 v[78:81], v[134:137], v[224:227], v[78:81]
	v_mfma_f32_16x16x32_bf16 v[74:77], v[142:145], v[224:227], v[74:77]
	s_setprio 0
	s_setprio 1
	v_mfma_f32_16x16x32_bf16 v[118:121], v[146:149], v[162:165], v[118:121]
	v_mfma_f32_16x16x32_bf16 v[114:117], v[154:157], v[162:165], v[114:117]
	v_mfma_f32_16x16x32_bf16 v[102:105], v[146:149], v[170:173], v[102:105]
	v_mfma_f32_16x16x32_bf16 v[98:101], v[154:157], v[170:173], v[98:101]
	v_mfma_f32_16x16x32_bf16 v[86:89], v[146:149], v[208:211], v[86:89]
	v_mfma_f32_16x16x32_bf16 v[82:85], v[154:157], v[208:211], v[82:85]
	v_mfma_f32_16x16x32_bf16 v[70:73], v[146:149], v[220:223], v[70:73]
	v_mfma_f32_16x16x32_bf16 v[66:69], v[154:157], v[220:223], v[66:69]
	v_mfma_f32_16x16x32_bf16 v[118:121], v[150:153], v[166:169], v[118:121]
	v_mfma_f32_16x16x32_bf16 v[114:117], v[158:161], v[166:169], v[114:117]
	v_mfma_f32_16x16x32_bf16 v[102:105], v[150:153], v[174:177], v[102:105]
	v_mfma_f32_16x16x32_bf16 v[98:101], v[158:161], v[174:177], v[98:101]
	v_mfma_f32_16x16x32_bf16 v[86:89], v[150:153], v[212:215], v[86:89]
	v_mfma_f32_16x16x32_bf16 v[82:85], v[158:161], v[212:215], v[82:85]
	v_mfma_f32_16x16x32_bf16 v[70:73], v[150:153], v[224:227], v[70:73]
	v_mfma_f32_16x16x32_bf16 v[66:69], v[158:161], v[224:227], v[66:69]
	s_barrier
; #define PG8_STAGE(bufoff, gbase, voff) do { _Pragma("unroll") for (int _i = 0; _i < 2; ++_i) \
;         __builtin_amdgcn_global_load_lds((const unsigned*)((const char*)(gbase) + (voff)[_i]), (PG8_LAS unsigned*)(lds + (bufoff) + ldsw + _i * 8192), 16, 0, 0); } while (0)
; #define PG8_LDA(dst, b, h) do { _Pragma("unroll") for (int m = 0; m < 4; ++m) _Pragma("unroll") for (int k = 0; k < 2; ++k) dst[m][k] = *(const PG8_LAS bf16x8*)(lds + PG8_SA(b, h) + aoff + m * 2048 + k * 1024); } while (0)
; #define PG8_MMA(ai, bj, At, Bt) do { __builtin_amdgcn_s_setprio(1); _Pragma("unroll") for (int m = 0; m < 4; ++m) _Pragma("unroll") for (int n = 0; n < 2; ++n) _Pragma("unroll") for (int k = 0; k < 2; ++k) \
;         acc[ai][bj][m][n] = __builtin_amdgcn_mfma_f32_16x16x32_bf16(Bt[n][k], At[m][k], acc[ai][bj][m][n], 0, 0, 0); __builtin_amdgcn_s_setprio(0); } while (0)
; #define PG8_WAIT_V(n) asm volatile("s_waitcnt vmcnt(" #n ")" ::: "memory")
; #define PG8_WAIT_L(n) asm volatile("s_waitcnt lgkmcnt(" #n ")" ::: "memory")
; #define PG8_BAR __builtin_amdgcn_s_barrier()
; #define PG8_SCHED __builtin_amdgcn_sched_barrier(0)
; template <class Epi, class Sched, bool ALIGN_EPI = false, bool SP2 = false>
; __device__ __forceinline__ void gemm_phase(PG8_LAS unsigned char* lds, const Gemm g, const Sched& S, const Epi& E) {
;     ...
;             PG8_LDA(At, 1, 1); PG8_STAGE(PG8_SB(1, 0), b3, voffB); PG8_STAGE(PG8_SB(1, 1), b3 + hstepB, voffB); PG8_STAGE(PG8_SA(1, 0), a3, voffA);
;             PG8_WAIT_V(8); PG8_WAIT_L(0); PG8_BAR; PG8_MMA(1, 0, At, B0); PG8_MMA(1, 1, At, B1); PG8_BAR; PG8_SCHED;
	s_setprio 0
	s_add_u32 s72, s70, 0x8000
	s_addc_u32 s73, s71, 0
	s_add_i32 s79, s79, s0
	v_lshl_add_u64 v[196:197], s[72:73], 0, v[180:181]
	s_mov_b32 m0, s79
	ds_read_b128 v[162:165], v203 offset:49152
	ds_read_b128 v[166:169], v203 offset:50176
	ds_read_b128 v[170:173], v203 offset:51200
	ds_read_b128 v[174:177], v203 offset:52224
	ds_read_b128 v[208:211], v203 offset:53248
	ds_read_b128 v[212:215], v203 offset:54272
	ds_read_b128 v[220:223], v203 offset:55296
	ds_read_b128 v[224:227], v203 offset:56320
	global_load_lds_dwordx4 v[196:197], off
	s_add_i32 m0, s79, 0x2000
	s_add_u32 s70, s70, 0x9000
	v_lshl_add_u64 v[196:197], s[72:73], 0, v[184:185]
	s_addc_u32 s71, s71, 0
	s_add_i32 s72, s80, s0
	global_load_lds_dwordx4 v[196:197], off
	v_lshl_add_u64 v[196:197], s[70:71], 0, v[180:181]
	s_mov_b32 m0, s72
	s_nop 0
	global_load_lds_dwordx4 v[196:197], off
	v_lshl_add_u64 v[196:197], s[70:71], 0, v[184:185]
	s_add_i32 m0, s72, 0x2000
	s_nop 0
	global_load_lds_dwordx4 v[196:197], off
	v_lshl_add_u64 v[196:197], s[68:69], 0, v[178:179]
	s_mov_b32 m0, s59
	s_nop 0
	global_load_lds_dwordx4 v[196:197], off
	v_lshl_add_u64 v[196:197], s[68:69], 0, v[182:183]
	s_mov_b32 m0, s74
	s_nop 0
	global_load_lds_dwordx4 v[196:197], off
	s_waitcnt vmcnt(8)
	s_waitcnt lgkmcnt(0)
	s_setprio 1
	s_barrier
	v_mfma_f32_16x16x32_bf16 v[62:65], v[130:133], v[162:165], v[62:65]
	v_mfma_f32_16x16x32_bf16 v[58:61], v[138:141], v[162:165], v[58:61]
	v_mfma_f32_16x16x32_bf16 v[46:49], v[130:133], v[170:173], v[46:49]
	v_mfma_f32_16x16x32_bf16 v[42:45], v[138:141], v[170:173], v[42:45]
	v_mfma_f32_16x16x32_bf16 v[30:33], v[130:133], v[208:211], v[30:33]
	v_mfma_f32_16x16x32_bf16 v[26:29], v[138:141], v[208:211], v[26:29]
	v_mfma_f32_16x16x32_bf16 v[14:17], v[130:133], v[220:223], v[14:17]
	v_mfma_f32_16x16x32_bf16 v[10:13], v[138:141], v[220:223], v[10:13]
	v_mfma_f32_16x16x32_bf16 v[62:65], v[134:137], v[166:169], v[62:65]
	v_mfma_f32_16x16x32_bf16 v[58:61], v[142:145], v[166:169], v[58:61]
	v_mfma_f32_16x16x32_bf16 v[46:49], v[134:137], v[174:177], v[46:49]
	v_mfma_f32_16x16x32_bf16 v[42:45], v[142:145], v[174:177], v[42:45]
	v_mfma_f32_16x16x32_bf16 v[30:33], v[134:137], v[212:215], v[30:33]
	v_mfma_f32_16x16x32_bf16 v[26:29], v[142:145], v[212:215], v[26:29]
	v_mfma_f32_16x16x32_bf16 v[14:17], v[134:137], v[224:227], v[14:17]
	v_mfma_f32_16x16x32_bf16 v[10:13], v[142:145], v[224:227], v[10:13]
	s_setprio 0
	s_setprio 1
	v_mfma_f32_16x16x32_bf16 v[54:57], v[146:149], v[162:165], v[54:57]
	v_mfma_f32_16x16x32_bf16 v[50:53], v[154:157], v[162:165], v[50:53]
	v_mfma_f32_16x16x32_bf16 v[38:41], v[146:149], v[170:173], v[38:41]
	v_mfma_f32_16x16x32_bf16 v[34:37], v[154:157], v[170:173], v[34:37]
	v_mfma_f32_16x16x32_bf16 v[22:25], v[146:149], v[208:211], v[22:25]
	v_mfma_f32_16x16x32_bf16 v[18:21], v[154:157], v[208:211], v[18:21]
	v_mfma_f32_16x16x32_bf16 v[6:9], v[146:149], v[220:223], v[6:9]
	v_mfma_f32_16x16x32_bf16 v[2:5], v[154:157], v[220:223], v[2:5]
	v_mfma_f32_16x16x32_bf16 v[54:57], v[150:153], v[166:169], v[54:57]
	v_mfma_f32_16x16x32_bf16 v[50:53], v[158:161], v[166:169], v[50:53]
	v_mfma_f32_16x16x32_bf16 v[38:41], v[150:153], v[174:177], v[38:41]
	v_mfma_f32_16x16x32_bf16 v[34:37], v[158:161], v[174:177], v[34:37]
	v_mfma_f32_16x16x32_bf16 v[22:25], v[150:153], v[212:215], v[22:25]
	v_mfma_f32_16x16x32_bf16 v[18:21], v[158:161], v[212:215], v[18:21]
	v_mfma_f32_16x16x32_bf16 v[6:9], v[150:153], v[224:227], v[6:9]
	v_mfma_f32_16x16x32_bf16 v[2:5], v[158:161], v[224:227], v[2:5]
	s_barrier
	s_setprio 0
	s_add_i32 s55, s55, 2
	s_add_u32 s50, s50, 0x10000
	s_addc_u32 s51, s51, 0
	s_add_u32 s53, s53, 0x10000
	s_addc_u32 s54, s54, 0
	s_cmp_gt_u32 s55, 13
	s_cbranch_scc0 .LBB0_477
	s_and_b64 vcc, exec, s[14:15]
	s_cbranch_vccz .LBB0_480
	s_barrier

; #define PG8_STAGE(bufoff, gbase, voff) do { _Pragma("unroll") for (int _i = 0; _i < 2; ++_i) \
;         __builtin_amdgcn_global_load_lds((const unsigned*)((const char*)(gbase) + (voff)[_i]), (PG8_LAS unsigned*)(lds + (bufoff) + ldsw + _i * 8192), 16, 0, 0); } while (0)
; #define PG8_LDA(dst, b, h) do { _Pragma("unroll") for (int m = 0; m < 4; ++m) _Pragma("unroll") for (int k = 0; k < 2; ++k) dst[m][k] = *(const PG8_LAS bf16x8*)(lds + PG8_SA(b, h) + aoff + m * 2048 + k * 1024); } while (0)
; #define PG8_LDB(dst, b, h) do { _Pragma("unroll") for (int n = 0; n < 2; ++n) _Pragma("unroll") for (int k = 0; k < 2; ++k) dst[n][k] = *(const PG8_LAS bf16x8*)(lds + PG8_SB(b, h) + boff + n * 2048 + k * 1024); } while (0)
; #define PG8_MMA(ai, bj, At, Bt) do { __builtin_amdgcn_s_setprio(1); _Pragma("unroll") for (int m = 0; m < 4; ++m) _Pragma("unroll") for (int n = 0; n < 2; ++n) _Pragma("unroll") for (int k = 0; k < 2; ++k) \
;         acc[ai][bj][m][n] = __builtin_amdgcn_mfma_f32_16x16x32_bf16(Bt[n][k], At[m][k], acc[ai][bj][m][n], 0, 0, 0); __builtin_amdgcn_s_setprio(0); } while (0)
; #define PG8_WAIT_V(n) asm volatile("s_waitcnt vmcnt(" #n ")" ::: "memory")
; #define PG8_WAIT_L(n) asm volatile("s_waitcnt lgkmcnt(" #n ")" ::: "memory")
; #define PG8_BAR __builtin_amdgcn_s_barrier()
; #define PG8_SCHED __builtin_amdgcn_sched_barrier(0)
; template <class Epi, class Sched, bool ALIGN_EPI = false, bool SP2 = false>
; __device__ __forceinline__ void gemm_phase(PG8_LAS unsigned char* lds, const Gemm g, const Sched& S, const Epi& E) {
;     ...
;             PG8_LDB(B0, 0, 0); PG8_LDB(B1, 0, 1); PG8_SCHED; PG8_LDA(At, 0, 0); PG8_STAGE(PG8_SA(1, 1), a1 + hstep, voffA);
;             PG8_WAIT_V(8); PG8_WAIT_L(0); PG8_BAR; PG8_MMA(0, 0, At, B0); PG8_MMA(0, 1, At, B1); PG8_BAR; PG8_SCHED;
;             PG8_LDA(At, 0, 1); PG8_STAGE(PG8_SB(0, 0), b2, voffB); PG8_STAGE(PG8_SB(0, 1), b2 + hstepB, voffB); PG8_STAGE(PG8_SA(0, 0), a2, voffA);
.LBB0_586:
	ds_read_b128 v[166:169], v153
	ds_read_b128 v[170:173], v153 offset:1024
	ds_read_b128 v[174:177], v153 offset:2048
	ds_read_b128 v[178:181], v153 offset:3072
	ds_read_b128 v[182:185], v154
	ds_read_b128 v[186:189], v154 offset:1024
	ds_read_b128 v[190:193], v154 offset:2048
	ds_read_b128 v[194:197], v154 offset:3072
	s_add_u32 s28, s26, 0x4000
	s_addc_u32 s29, s27, 0
	s_cmp_eq_u32 s59, 12
	s_cselect_b32 s42, s55, s28
	s_cselect_b32 s43, s19, s29
	s_cselect_b32 s36, s56, s57
	s_cselect_b32 s37, s17, s58
	s_add_u32 s28, s42, 0x8000
	s_addc_u32 s29, s43, 0
	v_lshl_add_u64 v[232:233], s[26:27], 0, v[142:143]
	s_add_i32 m0, s3, 0xc000
	ds_read_b128 v[198:201], v155
	ds_read_b128 v[202:205], v155 offset:1024
	ds_read_b128 v[206:209], v155 offset:2048
	ds_read_b128 v[210:213], v155 offset:3072
	ds_read_b128 v[214:217], v155 offset:4096
	ds_read_b128 v[220:223], v155 offset:5120
	ds_read_b128 v[224:227], v155 offset:6144
	ds_read_b128 v[228:231], v155 offset:7168
	global_load_lds_dwordx4 v[232:233], off
	v_lshl_add_u64 v[232:233], s[26:27], 0, v[144:145]
	s_add_i32 m0, s3, 0xe000
	s_nop 0
	global_load_lds_dwordx4 v[232:233], off
	s_waitcnt vmcnt(8)
	s_waitcnt lgkmcnt(0)
	s_setprio 1
	s_barrier
	v_mfma_f32_16x16x32_bf16 v[126:129], v[166:169], v[198:201], v[126:129]
	v_mfma_f32_16x16x32_bf16 v[122:125], v[174:177], v[198:201], v[122:125]
	v_mfma_f32_16x16x32_bf16 v[110:113], v[166:169], v[206:209], v[110:113]
	v_mfma_f32_16x16x32_bf16 v[106:109], v[174:177], v[206:209], v[106:109]
	v_mfma_f32_16x16x32_bf16 v[94:97], v[166:169], v[214:217], v[94:97]
	v_mfma_f32_16x16x32_bf16 v[90:93], v[174:177], v[214:217], v[90:93]
	v_mfma_f32_16x16x32_bf16 v[78:81], v[166:169], v[224:227], v[78:81]
	v_mfma_f32_16x16x32_bf16 v[74:77], v[174:177], v[224:227], v[74:77]
	v_mfma_f32_16x16x32_bf16 v[126:129], v[170:173], v[202:205], v[126:129]
	v_mfma_f32_16x16x32_bf16 v[122:125], v[178:181], v[202:205], v[122:125]
	v_mfma_f32_16x16x32_bf16 v[110:113], v[170:173], v[210:213], v[110:113]
	v_mfma_f32_16x16x32_bf16 v[106:109], v[178:181], v[210:213], v[106:109]
	v_mfma_f32_16x16x32_bf16 v[94:97], v[170:173], v[220:223], v[94:97]
	v_mfma_f32_16x16x32_bf16 v[90:93], v[178:181], v[220:223], v[90:93]
	v_mfma_f32_16x16x32_bf16 v[78:81], v[170:173], v[228:231], v[78:81]
	v_mfma_f32_16x16x32_bf16 v[74:77], v[178:181], v[228:231], v[74:77]
	s_setprio 0
	s_setprio 1
	v_mfma_f32_16x16x32_bf16 v[118:121], v[182:185], v[198:201], v[118:121]
	v_mfma_f32_16x16x32_bf16 v[114:117], v[190:193], v[198:201], v[114:117]
	v_mfma_f32_16x16x32_bf16 v[102:105], v[182:185], v[206:209], v[102:105]
	v_mfma_f32_16x16x32_bf16 v[98:101], v[190:193], v[206:209], v[98:101]
	v_mfma_f32_16x16x32_bf16 v[86:89], v[182:185], v[214:217], v[86:89]
	v_mfma_f32_16x16x32_bf16 v[82:85], v[190:193], v[214:217], v[82:85]
	v_mfma_f32_16x16x32_bf16 v[70:73], v[182:185], v[224:227], v[70:73]
	v_mfma_f32_16x16x32_bf16 v[66:69], v[190:193], v[224:227], v[66:69]
	v_mfma_f32_16x16x32_bf16 v[118:121], v[186:189], v[202:205], v[118:121]
	v_mfma_f32_16x16x32_bf16 v[114:117], v[194:197], v[202:205], v[114:117]
	v_mfma_f32_16x16x32_bf16 v[102:105], v[186:189], v[210:213], v[102:105]
	v_mfma_f32_16x16x32_bf16 v[98:101], v[194:197], v[210:213], v[98:101]
	v_mfma_f32_16x16x32_bf16 v[86:89], v[186:189], v[220:223], v[86:89]
	v_mfma_f32_16x16x32_bf16 v[82:85], v[194:197], v[220:223], v[82:85]
	v_mfma_f32_16x16x32_bf16 v[70:73], v[186:189], v[228:231], v[70:73]
	v_mfma_f32_16x16x32_bf16 v[66:69], v[194:197], v[228:231], v[66:69]
	s_barrier
	s_setprio 0
	s_add_i32 s66, s8, s1
	v_lshl_add_u64 v[232:233], s[36:37], 0, v[132:133]
	s_mov_b32 m0, s66
	ds_read_b128 v[198:201], v155 offset:16384
	ds_read_b128 v[202:205], v155 offset:17408
	ds_read_b128 v[206:209], v155 offset:18432
	ds_read_b128 v[210:213], v155 offset:19456
	ds_read_b128 v[214:217], v155 offset:20480
	ds_read_b128 v[220:223], v155 offset:21504
	ds_read_b128 v[224:227], v155 offset:22528
	ds_read_b128 v[228:231], v155 offset:23552
	global_load_lds_dwordx4 v[232:233], off
	s_add_i32 m0, s66, 0x2000
	s_add_u32 s66, s36, 0x1000
	v_lshl_add_u64 v[232:233], s[36:37], 0, v[136:137]
	s_addc_u32 s67, s37, 0
	s_add_i32 s68, s52, s1
	global_load_lds_dwordx4 v[232:233], off
	v_lshl_add_u64 v[232:233], s[66:67], 0, v[132:133]
	s_mov_b32 m0, s68
	s_nop 0
	global_load_lds_dwordx4 v[232:233], off
	v_lshl_add_u64 v[232:233], s[66:67], 0, v[136:137]
	s_add_i32 m0, s68, 0x2000
	s_nop 0
	global_load_lds_dwordx4 v[232:233], off
	v_lshl_add_u64 v[232:233], s[42:43], 0, v[130:131]
	s_mov_b32 m0, s3
	s_nop 0
	global_load_lds_dwordx4 v[232:233], off
	v_lshl_add_u64 v[232:233], s[42:43], 0, v[134:135]
	s_mov_b32 m0, s44
	s_nop 0
	global_load_lds_dwordx4 v[232:233], off
	s_waitcnt vmcnt(8)
	s_waitcnt lgkmcnt(0)
	s_setprio 1
	s_barrier
; #define PG8_STAGE(bufoff, gbase, voff) do { _Pragma("unroll") for (int _i = 0; _i < 2; ++_i) \
;         __builtin_amdgcn_global_load_lds((const unsigned*)((const char*)(gbase) + (voff)[_i]), (PG8_LAS unsigned*)(lds + (bufoff) + ldsw + _i * 8192), 16, 0, 0); } while (0)
; #define PG8_LDA(dst, b, h) do { _Pragma("unroll") for (int m = 0; m < 4; ++m) _Pragma("unroll") for (int k = 0; k < 2; ++k) dst[m][k] = *(const PG8_LAS bf16x8*)(lds + PG8_SA(b, h) + aoff + m * 2048 + k * 1024); } while (0)
; #define PG8_LDB(dst, b, h) do { _Pragma("unroll") for (int n = 0; n < 2; ++n) _Pragma("unroll") for (int k = 0; k < 2; ++k) dst[n][k] = *(const PG8_LAS bf16x8*)(lds + PG8_SB(b, h) + boff + n * 2048 + k * 1024); } while (0)
; #define PG8_MMA(ai, bj, At, Bt) do { __builtin_amdgcn_s_setprio(1); _Pragma("unroll") for (int m = 0; m < 4; ++m) _Pragma("unroll") for (int n = 0; n < 2; ++n) _Pragma("unroll") for (int k = 0; k < 2; ++k) \
;         acc[ai][bj][m][n] = __builtin_amdgcn_mfma_f32_16x16x32_bf16(Bt[n][k], At[m][k], acc[ai][bj][m][n], 0, 0, 0); __builtin_amdgcn_s_setprio(0); } while (0)
; #define PG8_WAIT_V(n) asm volatile("s_waitcnt vmcnt(" #n ")" ::: "memory")
; #define PG8_WAIT_L(n) asm volatile("s_waitcnt lgkmcnt(" #n ")" ::: "memory")
; #define PG8_BAR __builtin_amdgcn_s_barrier()
; #define PG8_SCHED __builtin_amdgcn_sched_barrier(0)
; template <class Epi, class Sched, bool ALIGN_EPI = false, bool SP2 = false>
; __device__ __forceinline__ void gemm_phase(PG8_LAS unsigned char* lds, const Gemm g, const Sched& S, const Epi& E) {
;     ...
;             PG8_WAIT_V(8); PG8_WAIT_L(0); PG8_BAR; PG8_MMA(1, 0, At, B0); PG8_MMA(1, 1, At, B1); PG8_BAR; PG8_SCHED;
;             PG8_LDB(B0, 1, 0); PG8_LDB(B1, 1, 1); PG8_SCHED; PG8_LDA(At, 1, 0); PG8_STAGE(PG8_SA(0, 1), a2 + hstep, voffA);
;             PG8_WAIT_V(8); PG8_WAIT_L(0); PG8_BAR; PG8_MMA(0, 0, At, B0); PG8_MMA(0, 1, At, B1); PG8_BAR; PG8_SCHED;
	v_mfma_f32_16x16x32_bf16 v[62:65], v[166:169], v[198:201], v[62:65]
	v_mfma_f32_16x16x32_bf16 v[58:61], v[174:177], v[198:201], v[58:61]
	v_mfma_f32_16x16x32_bf16 v[46:49], v[166:169], v[206:209], v[46:49]
	v_mfma_f32_16x16x32_bf16 v[42:45], v[174:177], v[206:209], v[42:45]
	v_mfma_f32_16x16x32_bf16 v[30:33], v[166:169], v[214:217], v[30:33]
	v_mfma_f32_16x16x32_bf16 v[26:29], v[174:177], v[214:217], v[26:29]
	v_mfma_f32_16x16x32_bf16 v[14:17], v[166:169], v[224:227], v[14:17]
	v_mfma_f32_16x16x32_bf16 v[10:13], v[174:177], v[224:227], v[10:13]
	v_mfma_f32_16x16x32_bf16 v[62:65], v[170:173], v[202:205], v[62:65]
	v_mfma_f32_16x16x32_bf16 v[58:61], v[178:181], v[202:205], v[58:61]
	v_mfma_f32_16x16x32_bf16 v[46:49], v[170:173], v[210:213], v[46:49]
	v_mfma_f32_16x16x32_bf16 v[42:45], v[178:181], v[210:213], v[42:45]
	v_mfma_f32_16x16x32_bf16 v[30:33], v[170:173], v[220:223], v[30:33]
	v_mfma_f32_16x16x32_bf16 v[26:29], v[178:181], v[220:223], v[26:29]
	v_mfma_f32_16x16x32_bf16 v[14:17], v[170:173], v[228:231], v[14:17]
	v_mfma_f32_16x16x32_bf16 v[10:13], v[178:181], v[228:231], v[10:13]
	s_setprio 0
	s_setprio 1
	v_mfma_f32_16x16x32_bf16 v[54:57], v[182:185], v[198:201], v[54:57]
	v_mfma_f32_16x16x32_bf16 v[50:53], v[190:193], v[198:201], v[50:53]
	v_mfma_f32_16x16x32_bf16 v[38:41], v[182:185], v[206:209], v[38:41]
	v_mfma_f32_16x16x32_bf16 v[34:37], v[190:193], v[206:209], v[34:37]
	v_mfma_f32_16x16x32_bf16 v[22:25], v[182:185], v[214:217], v[22:25]
	v_mfma_f32_16x16x32_bf16 v[18:21], v[190:193], v[214:217], v[18:21]
	v_mfma_f32_16x16x32_bf16 v[6:9], v[182:185], v[224:227], v[6:9]
	v_mfma_f32_16x16x32_bf16 v[2:5], v[190:193], v[224:227], v[2:5]
	v_mfma_f32_16x16x32_bf16 v[54:57], v[186:189], v[202:205], v[54:57]
	v_mfma_f32_16x16x32_bf16 v[50:53], v[194:197], v[202:205], v[50:53]
	v_mfma_f32_16x16x32_bf16 v[38:41], v[186:189], v[210:213], v[38:41]
	v_mfma_f32_16x16x32_bf16 v[34:37], v[194:197], v[210:213], v[34:37]
	v_mfma_f32_16x16x32_bf16 v[22:25], v[186:189], v[220:223], v[22:25]
	v_mfma_f32_16x16x32_bf16 v[18:21], v[194:197], v[220:223], v[18:21]
	v_mfma_f32_16x16x32_bf16 v[6:9], v[186:189], v[228:231], v[6:9]
	v_mfma_f32_16x16x32_bf16 v[2:5], v[194:197], v[228:231], v[2:5]
	s_barrier
	s_setprio 0
	s_add_i32 s66, 0, 0x18000
	v_add_u32_e32 v165, s66, v151
	s_add_i32 s67, 0, 0x1c000
	ds_read_b128 v[166:169], v165
	ds_read_b128 v[170:173], v165 offset:1024
	ds_read_b128 v[174:177], v165 offset:2048
	ds_read_b128 v[178:181], v165 offset:3072
	v_add_u32_e32 v165, s67, v151
	ds_read_b128 v[182:185], v165
	ds_read_b128 v[186:189], v165 offset:1024
	ds_read_b128 v[190:193], v165 offset:2048
	ds_read_b128 v[194:197], v165 offset:3072
	s_add_u32 s42, s42, 0x4000
	s_addc_u32 s43, s43, 0
	s_mov_b32 m0, s45
	v_lshl_add_u64 v[232:233], s[42:43], 0, v[130:131]
	ds_read_b128 v[198:201], v155 offset:32768
	ds_read_b128 v[202:205], v155 offset:33792
	ds_read_b128 v[206:209], v155 offset:34816
	ds_read_b128 v[210:213], v155 offset:35840
	ds_read_b128 v[214:217], v155 offset:36864
	ds_read_b128 v[220:223], v155 offset:37888
	ds_read_b128 v[224:227], v155 offset:38912
	ds_read_b128 v[228:231], v155 offset:39936
	global_load_lds_dwordx4 v[232:233], off
	v_lshl_add_u64 v[232:233], s[42:43], 0, v[134:135]
	s_mov_b32 m0, s46
	s_nop 0
	global_load_lds_dwordx4 v[232:233], off
	s_waitcnt vmcnt(8)
	s_waitcnt lgkmcnt(0)
	s_setprio 1
	s_barrier
	v_mfma_f32_16x16x32_bf16 v[126:129], v[166:169], v[198:201], v[126:129]
	v_mfma_f32_16x16x32_bf16 v[122:125], v[174:177], v[198:201], v[122:125]
	v_mfma_f32_16x16x32_bf16 v[110:113], v[166:169], v[206:209], v[110:113]
	v_mfma_f32_16x16x32_bf16 v[106:109], v[174:177], v[206:209], v[106:109]
	v_mfma_f32_16x16x32_bf16 v[94:97], v[166:169], v[214:217], v[94:97]
	v_mfma_f32_16x16x32_bf16 v[90:93], v[174:177], v[214:217], v[90:93]
	v_mfma_f32_16x16x32_bf16 v[78:81], v[166:169], v[224:227], v[78:81]
	v_mfma_f32_16x16x32_bf16 v[74:77], v[174:177], v[224:227], v[74:77]
	v_mfma_f32_16x16x32_bf16 v[126:129], v[170:173], v[202:205], v[126:129]
	v_mfma_f32_16x16x32_bf16 v[122:125], v[178:181], v[202:205], v[122:125]
	v_mfma_f32_16x16x32_bf16 v[110:113], v[170:173], v[210:213], v[110:113]
	v_mfma_f32_16x16x32_bf16 v[106:109], v[178:181], v[210:213], v[106:109]
	v_mfma_f32_16x16x32_bf16 v[94:97], v[170:173], v[220:223], v[94:97]
	v_mfma_f32_16x16x32_bf16 v[90:93], v[178:181], v[220:223], v[90:93]
	v_mfma_f32_16x16x32_bf16 v[78:81], v[170:173], v[228:231], v[78:81]
	v_mfma_f32_16x16x32_bf16 v[74:77], v[178:181], v[228:231], v[74:77]
	s_setprio 0
	s_setprio 1
	v_mfma_f32_16x16x32_bf16 v[118:121], v[182:185], v[198:201], v[118:121]
	v_mfma_f32_16x16x32_bf16 v[114:117], v[190:193], v[198:201], v[114:117]
	v_mfma_f32_16x16x32_bf16 v[102:105], v[182:185], v[206:209], v[102:105]
	v_mfma_f32_16x16x32_bf16 v[98:101], v[190:193], v[206:209], v[98:101]
	v_mfma_f32_16x16x32_bf16 v[86:89], v[182:185], v[214:217], v[86:89]
	v_mfma_f32_16x16x32_bf16 v[82:85], v[190:193], v[214:217], v[82:85]
	v_mfma_f32_16x16x32_bf16 v[70:73], v[182:185], v[224:227], v[70:73]
	v_mfma_f32_16x16x32_bf16 v[66:69], v[190:193], v[224:227], v[66:69]
	v_mfma_f32_16x16x32_bf16 v[118:121], v[186:189], v[202:205], v[118:121]
	v_mfma_f32_16x16x32_bf16 v[114:117], v[194:197], v[202:205], v[114:117]
	v_mfma_f32_16x16x32_bf16 v[102:105], v[186:189], v[210:213], v[102:105]
	v_mfma_f32_16x16x32_bf16 v[98:101], v[194:197], v[210:213], v[98:101]
	v_mfma_f32_16x16x32_bf16 v[86:89], v[186:189], v[220:223], v[86:89]
	v_mfma_f32_16x16x32_bf16 v[82:85], v[194:197], v[220:223], v[82:85]
	v_mfma_f32_16x16x32_bf16 v[70:73], v[186:189], v[228:231], v[70:73]
	v_mfma_f32_16x16x32_bf16 v[66:69], v[194:197], v[228:231], v[66:69]
	s_barrier
; #define PG8_STAGE(bufoff, gbase, voff) do { _Pragma("unroll") for (int _i = 0; _i < 2; ++_i) \
;         __builtin_amdgcn_global_load_lds((const unsigned*)((const char*)(gbase) + (voff)[_i]), (PG8_LAS unsigned*)(lds + (bufoff) + ldsw + _i * 8192), 16, 0, 0); } while (0)
; #define PG8_LDA(dst, b, h) do { _Pragma("unroll") for (int m = 0; m < 4; ++m) _Pragma("unroll") for (int k = 0; k < 2; ++k) dst[m][k] = *(const PG8_LAS bf16x8*)(lds + PG8_SA(b, h) + aoff + m * 2048 + k * 1024); } while (0)
; #define PG8_MMA(ai, bj, At, Bt) do { __builtin_amdgcn_s_setprio(1); _Pragma("unroll") for (int m = 0; m < 4; ++m) _Pragma("unroll") for (int n = 0; n < 2; ++n) _Pragma("unroll") for (int k = 0; k < 2; ++k) \
;         acc[ai][bj][m][n] = __builtin_amdgcn_mfma_f32_16x16x32_bf16(Bt[n][k], At[m][k], acc[ai][bj][m][n], 0, 0, 0); __builtin_amdgcn_s_setprio(0); } while (0)
; #define PG8_WAIT_V(n) asm volatile("s_waitcnt vmcnt(" #n ")" ::: "memory")
; #define PG8_WAIT_L(n) asm volatile("s_waitcnt lgkmcnt(" #n ")" ::: "memory")
; #define PG8_BAR __builtin_amdgcn_s_barrier()
; #define PG8_SCHED __builtin_amdgcn_sched_barrier(0)
; template <class Epi, class Sched, bool ALIGN_EPI = false, bool SP2 = false>
; __device__ __forceinline__ void gemm_phase(PG8_LAS unsigned char* lds, const Gemm g, const Sched& S, const Epi& E) {
;     ...
;             PG8_LDA(At, 1, 1); PG8_STAGE(PG8_SB(1, 0), b3, voffB); PG8_STAGE(PG8_SB(1, 1), b3 + hstepB, voffB); PG8_STAGE(PG8_SA(1, 0), a3, voffA);
;             PG8_WAIT_V(8); PG8_WAIT_L(0); PG8_BAR; PG8_MMA(1, 0, At, B0); PG8_MMA(1, 1, At, B1); PG8_BAR; PG8_SCHED;
	s_setprio 0
	s_add_u32 s42, s36, 0x8000
	s_addc_u32 s43, s37, 0
	s_add_i32 s66, s66, s1
	v_lshl_add_u64 v[232:233], s[42:43], 0, v[132:133]
	s_mov_b32 m0, s66
	ds_read_b128 v[198:201], v155 offset:49152
	ds_read_b128 v[202:205], v155 offset:50176
	ds_read_b128 v[206:209], v155 offset:51200
	ds_read_b128 v[210:213], v155 offset:52224
	ds_read_b128 v[214:217], v155 offset:53248
	ds_read_b128 v[220:223], v155 offset:54272
	ds_read_b128 v[224:227], v155 offset:55296
	ds_read_b128 v[228:231], v155 offset:56320
	global_load_lds_dwordx4 v[232:233], off
	s_add_i32 m0, s66, 0x2000
	s_add_u32 s36, s36, 0x9000
	v_lshl_add_u64 v[232:233], s[42:43], 0, v[136:137]
	s_addc_u32 s37, s37, 0
	s_add_i32 s42, s67, s1
	global_load_lds_dwordx4 v[232:233], off
	v_lshl_add_u64 v[232:233], s[36:37], 0, v[132:133]
	s_mov_b32 m0, s42
	s_nop 0
	global_load_lds_dwordx4 v[232:233], off
	v_lshl_add_u64 v[232:233], s[36:37], 0, v[136:137]
	s_add_i32 m0, s42, 0x2000
	s_nop 0
	global_load_lds_dwordx4 v[232:233], off
	v_lshl_add_u64 v[232:233], s[28:29], 0, v[130:131]
	s_mov_b32 m0, s49
	s_nop 0
	global_load_lds_dwordx4 v[232:233], off
	v_lshl_add_u64 v[232:233], s[28:29], 0, v[134:135]
	s_mov_b32 m0, s50
	s_nop 0
	global_load_lds_dwordx4 v[232:233], off
	s_waitcnt vmcnt(8)
	s_waitcnt lgkmcnt(0)
	s_setprio 1
	s_barrier
	v_mfma_f32_16x16x32_bf16 v[62:65], v[166:169], v[198:201], v[62:65]
	v_mfma_f32_16x16x32_bf16 v[58:61], v[174:177], v[198:201], v[58:61]
	v_mfma_f32_16x16x32_bf16 v[46:49], v[166:169], v[206:209], v[46:49]
	v_mfma_f32_16x16x32_bf16 v[42:45], v[174:177], v[206:209], v[42:45]
	v_mfma_f32_16x16x32_bf16 v[30:33], v[166:169], v[214:217], v[30:33]
	v_mfma_f32_16x16x32_bf16 v[26:29], v[174:177], v[214:217], v[26:29]
	v_mfma_f32_16x16x32_bf16 v[14:17], v[166:169], v[224:227], v[14:17]
	v_mfma_f32_16x16x32_bf16 v[10:13], v[174:177], v[224:227], v[10:13]
	v_mfma_f32_16x16x32_bf16 v[62:65], v[170:173], v[202:205], v[62:65]
	v_mfma_f32_16x16x32_bf16 v[58:61], v[178:181], v[202:205], v[58:61]
	v_mfma_f32_16x16x32_bf16 v[46:49], v[170:173], v[210:213], v[46:49]
	v_mfma_f32_16x16x32_bf16 v[42:45], v[178:181], v[210:213], v[42:45]
	v_mfma_f32_16x16x32_bf16 v[30:33], v[170:173], v[220:223], v[30:33]
	v_mfma_f32_16x16x32_bf16 v[26:29], v[178:181], v[220:223], v[26:29]
	v_mfma_f32_16x16x32_bf16 v[14:17], v[170:173], v[228:231], v[14:17]
	v_mfma_f32_16x16x32_bf16 v[10:13], v[178:181], v[228:231], v[10:13]
	s_setprio 0
	s_setprio 1
	v_mfma_f32_16x16x32_bf16 v[54:57], v[182:185], v[198:201], v[54:57]
	v_mfma_f32_16x16x32_bf16 v[50:53], v[190:193], v[198:201], v[50:53]
	v_mfma_f32_16x16x32_bf16 v[38:41], v[182:185], v[206:209], v[38:41]
	v_mfma_f32_16x16x32_bf16 v[34:37], v[190:193], v[206:209], v[34:37]
	v_mfma_f32_16x16x32_bf16 v[22:25], v[182:185], v[214:217], v[22:25]
	v_mfma_f32_16x16x32_bf16 v[18:21], v[190:193], v[214:217], v[18:21]
	v_mfma_f32_16x16x32_bf16 v[6:9], v[182:185], v[224:227], v[6:9]
	v_mfma_f32_16x16x32_bf16 v[2:5], v[190:193], v[224:227], v[2:5]
	v_mfma_f32_16x16x32_bf16 v[54:57], v[186:189], v[202:205], v[54:57]
	v_mfma_f32_16x16x32_bf16 v[50:53], v[194:197], v[202:205], v[50:53]
	v_mfma_f32_16x16x32_bf16 v[38:41], v[186:189], v[210:213], v[38:41]
	v_mfma_f32_16x16x32_bf16 v[34:37], v[194:197], v[210:213], v[34:37]
	v_mfma_f32_16x16x32_bf16 v[22:25], v[186:189], v[220:223], v[22:25]
	v_mfma_f32_16x16x32_bf16 v[18:21], v[194:197], v[220:223], v[18:21]
	v_mfma_f32_16x16x32_bf16 v[6:9], v[186:189], v[228:231], v[6:9]
	v_mfma_f32_16x16x32_bf16 v[2:5], v[194:197], v[228:231], v[2:5]
	s_barrier
	s_setprio 0
	s_add_i32 s59, s59, 2
	s_add_u32 s26, s26, 0x10000
	s_addc_u32 s27, s27, 0
	s_add_u32 s57, s57, 0x10000
	s_addc_u32 s58, s58, 0
	s_cmp_gt_u32 s59, 13
	s_cbranch_scc0 .LBB0_586
	s_and_b64 vcc, exec, s[12:13]
	s_cbranch_vccz .LBB0_589
	s_barrier

; #define PG8_STAGE(bufoff, gbase, voff) do { _Pragma("unroll") for (int _i = 0; _i < 2; ++_i) \
;         __builtin_amdgcn_global_load_lds((const unsigned*)((const char*)(gbase) + (voff)[_i]), (PG8_LAS unsigned*)(lds + (bufoff) + ldsw + _i * 8192), 16, 0, 0); } while (0)
; #define PG8_LDA(dst, b, h) do { _Pragma("unroll") for (int m = 0; m < 4; ++m) _Pragma("unroll") for (int k = 0; k < 2; ++k) dst[m][k] = *(const PG8_LAS bf16x8*)(lds + PG8_SA(b, h) + aoff + m * 2048 + k * 1024); } while (0)
; #define PG8_LDB(dst, b, h) do { _Pragma("unroll") for (int n = 0; n < 2; ++n) _Pragma("unroll") for (int k = 0; k < 2; ++k) dst[n][k] = *(const PG8_LAS bf16x8*)(lds + PG8_SB(b, h) + boff + n * 2048 + k * 1024); } while (0)
; #define PG8_MMA(ai, bj, At, Bt) do { __builtin_amdgcn_s_setprio(1); _Pragma("unroll") for (int m = 0; m < 4; ++m) _Pragma("unroll") for (int n = 0; n < 2; ++n) _Pragma("unroll") for (int k = 0; k < 2; ++k) \
;         acc[ai][bj][m][n] = __builtin_amdgcn_mfma_f32_16x16x32_bf16(Bt[n][k], At[m][k], acc[ai][bj][m][n], 0, 0, 0); __builtin_amdgcn_s_setprio(0); } while (0)
; #define PG8_WAIT_V(n) asm volatile("s_waitcnt vmcnt(" #n ")" ::: "memory")
; #define PG8_WAIT_L(n) asm volatile("s_waitcnt lgkmcnt(" #n ")" ::: "memory")
; #define PG8_BAR __builtin_amdgcn_s_barrier()
; #define PG8_SCHED __builtin_amdgcn_sched_barrier(0)
; template <class Epi, class Sched, bool ALIGN_EPI = false, bool SP2 = false>
; __device__ __forceinline__ void gemm_phase(PG8_LAS unsigned char* lds, const Gemm g, const Sched& S, const Epi& E) {
;     ...
;             PG8_LDB(B0, 0, 0); PG8_LDB(B1, 0, 1); PG8_SCHED; PG8_LDA(At, 0, 0); PG8_STAGE(PG8_SA(1, 1), a1 + hstep, voffA);
;             PG8_WAIT_V(8); PG8_WAIT_L(0); PG8_BAR; PG8_MMA(0, 0, At, B0); PG8_MMA(0, 1, At, B1); PG8_BAR; PG8_SCHED;
;             PG8_LDA(At, 0, 1); PG8_STAGE(PG8_SB(0, 0), b2, voffB); PG8_STAGE(PG8_SB(0, 1), b2 + hstepB, voffB); PG8_STAGE(PG8_SA(0, 0), a2, voffA);
.LBB0_682:
	ds_read_b128 v[98:101], v215
	ds_read_b128 v[102:105], v215 offset:1024
	ds_read_b128 v[122:125], v215 offset:2048
	ds_read_b128 v[126:129], v215 offset:3072
	ds_read_b128 v[146:149], v216
	ds_read_b128 v[150:153], v216 offset:1024
	ds_read_b128 v[154:157], v216 offset:2048
	ds_read_b128 v[158:161], v216 offset:3072
	s_add_u32 s42, s36, 0x4000
	s_addc_u32 s43, s37, 0
	s_cmp_eq_u32 s54, 60
	s_cselect_b32 s46, s23, s42
	s_cselect_b32 s47, s9, s43
	s_cselect_b32 s44, s29, s52
	s_cselect_b32 s45, s21, s53
	s_add_u32 s42, s46, 0x8000
	s_addc_u32 s43, s47, 0
	v_lshl_add_u64 v[230:231], s[36:37], 0, v[198:199]
	s_add_i32 m0, s1, 0xc000
	ds_read_b128 v[162:165], v217
	ds_read_b128 v[166:169], v217 offset:1024
	ds_read_b128 v[170:173], v217 offset:2048
	ds_read_b128 v[174:177], v217 offset:3072
	ds_read_b128 v[178:181], v217 offset:4096
	ds_read_b128 v[182:185], v217 offset:5120
	ds_read_b128 v[222:225], v217 offset:6144
	ds_read_b128 v[226:229], v217 offset:7168
	global_load_lds_dwordx4 v[230:231], off
	v_lshl_add_u64 v[230:231], s[36:37], 0, v[200:201]
	s_add_i32 m0, s1, 0xe000
	s_nop 0
	global_load_lds_dwordx4 v[230:231], off
	s_waitcnt vmcnt(8)
	s_waitcnt lgkmcnt(0)
	s_setprio 1
	s_barrier
	v_mfma_f32_16x16x32_bf16 v[142:145], v[98:101], v[162:165], v[142:145]
	v_mfma_f32_16x16x32_bf16 v[138:141], v[122:125], v[162:165], v[138:141]
	v_mfma_f32_16x16x32_bf16 v[118:121], v[98:101], v[170:173], v[118:121]
	v_mfma_f32_16x16x32_bf16 v[114:117], v[122:125], v[170:173], v[114:117]
	v_mfma_f32_16x16x32_bf16 v[94:97], v[98:101], v[178:181], v[94:97]
	v_mfma_f32_16x16x32_bf16 v[90:93], v[122:125], v[178:181], v[90:93]
	v_mfma_f32_16x16x32_bf16 v[78:81], v[98:101], v[222:225], v[78:81]
	v_mfma_f32_16x16x32_bf16 v[74:77], v[122:125], v[222:225], v[74:77]
	v_mfma_f32_16x16x32_bf16 v[142:145], v[102:105], v[166:169], v[142:145]
	v_mfma_f32_16x16x32_bf16 v[138:141], v[126:129], v[166:169], v[138:141]
	v_mfma_f32_16x16x32_bf16 v[118:121], v[102:105], v[174:177], v[118:121]
	v_mfma_f32_16x16x32_bf16 v[114:117], v[126:129], v[174:177], v[114:117]
	v_mfma_f32_16x16x32_bf16 v[94:97], v[102:105], v[182:185], v[94:97]
	v_mfma_f32_16x16x32_bf16 v[90:93], v[126:129], v[182:185], v[90:93]
	v_mfma_f32_16x16x32_bf16 v[78:81], v[102:105], v[226:229], v[78:81]
	v_mfma_f32_16x16x32_bf16 v[74:77], v[126:129], v[226:229], v[74:77]
	s_setprio 0
	s_setprio 1
	v_mfma_f32_16x16x32_bf16 v[134:137], v[146:149], v[162:165], v[134:137]
	v_mfma_f32_16x16x32_bf16 v[130:133], v[154:157], v[162:165], v[130:133]
	v_mfma_f32_16x16x32_bf16 v[110:113], v[146:149], v[170:173], v[110:113]
	v_mfma_f32_16x16x32_bf16 v[106:109], v[154:157], v[170:173], v[106:109]
	v_mfma_f32_16x16x32_bf16 v[86:89], v[146:149], v[178:181], v[86:89]
	v_mfma_f32_16x16x32_bf16 v[82:85], v[154:157], v[178:181], v[82:85]
	v_mfma_f32_16x16x32_bf16 v[70:73], v[146:149], v[222:225], v[70:73]
	v_mfma_f32_16x16x32_bf16 v[66:69], v[154:157], v[222:225], v[66:69]
	v_mfma_f32_16x16x32_bf16 v[134:137], v[150:153], v[166:169], v[134:137]
	v_mfma_f32_16x16x32_bf16 v[130:133], v[158:161], v[166:169], v[130:133]
	v_mfma_f32_16x16x32_bf16 v[110:113], v[150:153], v[174:177], v[110:113]
	v_mfma_f32_16x16x32_bf16 v[106:109], v[158:161], v[174:177], v[106:109]
	v_mfma_f32_16x16x32_bf16 v[86:89], v[150:153], v[182:185], v[86:89]
	v_mfma_f32_16x16x32_bf16 v[82:85], v[158:161], v[182:185], v[82:85]
	v_mfma_f32_16x16x32_bf16 v[70:73], v[150:153], v[226:229], v[70:73]
	v_mfma_f32_16x16x32_bf16 v[66:69], v[158:161], v[226:229], v[66:69]
	s_barrier
	s_setprio 0
	s_add_i32 s55, s59, s0
	v_lshl_add_u64 v[230:231], s[44:45], 0, v[188:189]
	s_mov_b32 m0, s55
	ds_read_b128 v[162:165], v217 offset:16384
	ds_read_b128 v[166:169], v217 offset:17408
	ds_read_b128 v[170:173], v217 offset:18432
	ds_read_b128 v[174:177], v217 offset:19456
	ds_read_b128 v[178:181], v217 offset:20480
	ds_read_b128 v[182:185], v217 offset:21504
	ds_read_b128 v[222:225], v217 offset:22528
	ds_read_b128 v[226:229], v217 offset:23552
	global_load_lds_dwordx4 v[230:231], off
	s_add_i32 m0, s55, 0x2000
	s_add_u32 s68, s44, 0x1000
	v_lshl_add_u64 v[230:231], s[44:45], 0, v[192:193]
	s_addc_u32 s69, s45, 0
	s_add_i32 s55, s64, s0
	global_load_lds_dwordx4 v[230:231], off
	v_lshl_add_u64 v[230:231], s[68:69], 0, v[188:189]
	s_mov_b32 m0, s55
	s_nop 0
	global_load_lds_dwordx4 v[230:231], off
	v_lshl_add_u64 v[230:231], s[68:69], 0, v[192:193]
	s_add_i32 m0, s55, 0x2000
	s_nop 0
	global_load_lds_dwordx4 v[230:231], off
	v_lshl_add_u64 v[230:231], s[46:47], 0, v[186:187]
	s_mov_b32 m0, s1
	s_nop 0
	global_load_lds_dwordx4 v[230:231], off
	v_lshl_add_u64 v[230:231], s[46:47], 0, v[190:191]
	s_mov_b32 m0, s3
	s_nop 0
	global_load_lds_dwordx4 v[230:231], off
	s_waitcnt vmcnt(8)
	s_waitcnt lgkmcnt(0)
	s_setprio 1
	s_barrier
; #define PG8_STAGE(bufoff, gbase, voff) do { _Pragma("unroll") for (int _i = 0; _i < 2; ++_i) \
;         __builtin_amdgcn_global_load_lds((const unsigned*)((const char*)(gbase) + (voff)[_i]), (PG8_LAS unsigned*)(lds + (bufoff) + ldsw + _i * 8192), 16, 0, 0); } while (0)
; #define PG8_LDA(dst, b, h) do { _Pragma("unroll") for (int m = 0; m < 4; ++m) _Pragma("unroll") for (int k = 0; k < 2; ++k) dst[m][k] = *(const PG8_LAS bf16x8*)(lds + PG8_SA(b, h) + aoff + m * 2048 + k * 1024); } while (0)
; #define PG8_LDB(dst, b, h) do { _Pragma("unroll") for (int n = 0; n < 2; ++n) _Pragma("unroll") for (int k = 0; k < 2; ++k) dst[n][k] = *(const PG8_LAS bf16x8*)(lds + PG8_SB(b, h) + boff + n * 2048 + k * 1024); } while (0)
; #define PG8_MMA(ai, bj, At, Bt) do { __builtin_amdgcn_s_setprio(1); _Pragma("unroll") for (int m = 0; m < 4; ++m) _Pragma("unroll") for (int n = 0; n < 2; ++n) _Pragma("unroll") for (int k = 0; k < 2; ++k) \
;         acc[ai][bj][m][n] = __builtin_amdgcn_mfma_f32_16x16x32_bf16(Bt[n][k], At[m][k], acc[ai][bj][m][n], 0, 0, 0); __builtin_amdgcn_s_setprio(0); } while (0)
; #define PG8_WAIT_V(n) asm volatile("s_waitcnt vmcnt(" #n ")" ::: "memory")
; #define PG8_WAIT_L(n) asm volatile("s_waitcnt lgkmcnt(" #n ")" ::: "memory")
; #define PG8_BAR __builtin_amdgcn_s_barrier()
; #define PG8_SCHED __builtin_amdgcn_sched_barrier(0)
; template <class Epi, class Sched, bool ALIGN_EPI = false, bool SP2 = false>
; __device__ __forceinline__ void gemm_phase(PG8_LAS unsigned char* lds, const Gemm g, const Sched& S, const Epi& E) {
;     ...
;             PG8_LDA(At, 0, 1); PG8_STAGE(PG8_SB(0, 0), b2, voffB); PG8_STAGE(PG8_SB(0, 1), b2 + hstepB, voffB); PG8_STAGE(PG8_SA(0, 0), a2, voffA);
;             PG8_WAIT_V(8); PG8_WAIT_L(0); PG8_BAR; PG8_MMA(1, 0, At, B0); PG8_MMA(1, 1, At, B1); PG8_BAR; PG8_SCHED;
;             PG8_LDB(B0, 1, 0); PG8_LDB(B1, 1, 1); PG8_SCHED; PG8_LDA(At, 1, 0); PG8_STAGE(PG8_SA(0, 1), a2 + hstep, voffA);
;             PG8_WAIT_V(8); PG8_WAIT_L(0); PG8_BAR; PG8_MMA(0, 0, At, B0); PG8_MMA(0, 1, At, B1); PG8_BAR; PG8_SCHED;
	v_mfma_f32_16x16x32_bf16 v[62:65], v[98:101], v[162:165], v[62:65]
	v_mfma_f32_16x16x32_bf16 v[58:61], v[122:125], v[162:165], v[58:61]
	v_mfma_f32_16x16x32_bf16 v[46:49], v[98:101], v[170:173], v[46:49]
	v_mfma_f32_16x16x32_bf16 v[42:45], v[122:125], v[170:173], v[42:45]
	v_mfma_f32_16x16x32_bf16 v[30:33], v[98:101], v[178:181], v[30:33]
	v_mfma_f32_16x16x32_bf16 v[26:29], v[122:125], v[178:181], v[26:29]
	v_mfma_f32_16x16x32_bf16 v[14:17], v[98:101], v[222:225], v[14:17]
	v_mfma_f32_16x16x32_bf16 v[10:13], v[122:125], v[222:225], v[10:13]
	v_mfma_f32_16x16x32_bf16 v[62:65], v[102:105], v[166:169], v[62:65]
	v_mfma_f32_16x16x32_bf16 v[58:61], v[126:129], v[166:169], v[58:61]
	v_mfma_f32_16x16x32_bf16 v[46:49], v[102:105], v[174:177], v[46:49]
	v_mfma_f32_16x16x32_bf16 v[42:45], v[126:129], v[174:177], v[42:45]
	v_mfma_f32_16x16x32_bf16 v[30:33], v[102:105], v[182:185], v[30:33]
	v_mfma_f32_16x16x32_bf16 v[26:29], v[126:129], v[182:185], v[26:29]
	v_mfma_f32_16x16x32_bf16 v[14:17], v[102:105], v[226:229], v[14:17]
	v_mfma_f32_16x16x32_bf16 v[10:13], v[126:129], v[226:229], v[10:13]
	s_setprio 0
	s_setprio 1
	v_mfma_f32_16x16x32_bf16 v[54:57], v[146:149], v[162:165], v[54:57]
	v_mfma_f32_16x16x32_bf16 v[50:53], v[154:157], v[162:165], v[50:53]
	v_mfma_f32_16x16x32_bf16 v[38:41], v[146:149], v[170:173], v[38:41]
	v_mfma_f32_16x16x32_bf16 v[34:37], v[154:157], v[170:173], v[34:37]
	v_mfma_f32_16x16x32_bf16 v[22:25], v[146:149], v[178:181], v[22:25]
	v_mfma_f32_16x16x32_bf16 v[18:21], v[154:157], v[178:181], v[18:21]
	v_mfma_f32_16x16x32_bf16 v[6:9], v[146:149], v[222:225], v[6:9]
	v_mfma_f32_16x16x32_bf16 v[2:5], v[154:157], v[222:225], v[2:5]
	v_mfma_f32_16x16x32_bf16 v[54:57], v[150:153], v[166:169], v[54:57]
	v_mfma_f32_16x16x32_bf16 v[50:53], v[158:161], v[166:169], v[50:53]
	v_mfma_f32_16x16x32_bf16 v[38:41], v[150:153], v[174:177], v[38:41]
	v_mfma_f32_16x16x32_bf16 v[34:37], v[158:161], v[174:177], v[34:37]
	v_mfma_f32_16x16x32_bf16 v[22:25], v[150:153], v[182:185], v[22:25]
	v_mfma_f32_16x16x32_bf16 v[18:21], v[158:161], v[182:185], v[18:21]
	v_mfma_f32_16x16x32_bf16 v[6:9], v[150:153], v[226:229], v[6:9]
	v_mfma_f32_16x16x32_bf16 v[2:5], v[158:161], v[226:229], v[2:5]
	s_barrier
	s_setprio 0
	s_add_i32 s55, 0, 0x18000
	s_add_i32 s67, 0, 0x1c000
	v_add_u32_e32 v126, s55, v214
	v_add_u32_e32 v158, s67, v214
	ds_read_b128 v[98:101], v126
	ds_read_b128 v[102:105], v126 offset:1024
	ds_read_b128 v[122:125], v126 offset:2048
	ds_read_b128 v[126:129], v126 offset:3072
	ds_read_b128 v[146:149], v158
	ds_read_b128 v[150:153], v158 offset:1024
	ds_read_b128 v[154:157], v158 offset:2048
	ds_read_b128 v[158:161], v158 offset:3072
	s_add_u32 s46, s46, 0x4000
	s_addc_u32 s47, s47, 0
	s_mov_b32 m0, s48
	v_lshl_add_u64 v[230:231], s[46:47], 0, v[186:187]
	ds_read_b128 v[162:165], v217 offset:32768
	ds_read_b128 v[166:169], v217 offset:33792
	ds_read_b128 v[170:173], v217 offset:34816
	ds_read_b128 v[174:177], v217 offset:35840
	ds_read_b128 v[178:181], v217 offset:36864
	ds_read_b128 v[182:185], v217 offset:37888
	ds_read_b128 v[222:225], v217 offset:38912
	ds_read_b128 v[226:229], v217 offset:39936
	global_load_lds_dwordx4 v[230:231], off
	v_lshl_add_u64 v[230:231], s[46:47], 0, v[190:191]
	s_mov_b32 m0, s49
	s_nop 0
	global_load_lds_dwordx4 v[230:231], off
	s_waitcnt vmcnt(8)
	s_waitcnt lgkmcnt(0)
	s_setprio 1
	s_barrier
	v_mfma_f32_16x16x32_bf16 v[142:145], v[98:101], v[162:165], v[142:145]
	v_mfma_f32_16x16x32_bf16 v[138:141], v[122:125], v[162:165], v[138:141]
	v_mfma_f32_16x16x32_bf16 v[118:121], v[98:101], v[170:173], v[118:121]
	v_mfma_f32_16x16x32_bf16 v[114:117], v[122:125], v[170:173], v[114:117]
	v_mfma_f32_16x16x32_bf16 v[94:97], v[98:101], v[178:181], v[94:97]
	v_mfma_f32_16x16x32_bf16 v[90:93], v[122:125], v[178:181], v[90:93]
	v_mfma_f32_16x16x32_bf16 v[78:81], v[98:101], v[222:225], v[78:81]
	v_mfma_f32_16x16x32_bf16 v[74:77], v[122:125], v[222:225], v[74:77]
	v_mfma_f32_16x16x32_bf16 v[142:145], v[102:105], v[166:169], v[142:145]
	v_mfma_f32_16x16x32_bf16 v[138:141], v[126:129], v[166:169], v[138:141]
	v_mfma_f32_16x16x32_bf16 v[118:121], v[102:105], v[174:177], v[118:121]
	v_mfma_f32_16x16x32_bf16 v[114:117], v[126:129], v[174:177], v[114:117]
	v_mfma_f32_16x16x32_bf16 v[94:97], v[102:105], v[182:185], v[94:97]
	v_mfma_f32_16x16x32_bf16 v[90:93], v[126:129], v[182:185], v[90:93]
	v_mfma_f32_16x16x32_bf16 v[78:81], v[102:105], v[226:229], v[78:81]
	v_mfma_f32_16x16x32_bf16 v[74:77], v[126:129], v[226:229], v[74:77]
	s_setprio 0
	s_setprio 1
	v_mfma_f32_16x16x32_bf16 v[134:137], v[146:149], v[162:165], v[134:137]
	v_mfma_f32_16x16x32_bf16 v[130:133], v[154:157], v[162:165], v[130:133]
	v_mfma_f32_16x16x32_bf16 v[110:113], v[146:149], v[170:173], v[110:113]
	v_mfma_f32_16x16x32_bf16 v[106:109], v[154:157], v[170:173], v[106:109]
	v_mfma_f32_16x16x32_bf16 v[86:89], v[146:149], v[178:181], v[86:89]
	v_mfma_f32_16x16x32_bf16 v[82:85], v[154:157], v[178:181], v[82:85]
	v_mfma_f32_16x16x32_bf16 v[70:73], v[146:149], v[222:225], v[70:73]
	v_mfma_f32_16x16x32_bf16 v[66:69], v[154:157], v[222:225], v[66:69]
	v_mfma_f32_16x16x32_bf16 v[134:137], v[150:153], v[166:169], v[134:137]
	v_mfma_f32_16x16x32_bf16 v[130:133], v[158:161], v[166:169], v[130:133]
	v_mfma_f32_16x16x32_bf16 v[110:113], v[150:153], v[174:177], v[110:113]
	v_mfma_f32_16x16x32_bf16 v[106:109], v[158:161], v[174:177], v[106:109]
	v_mfma_f32_16x16x32_bf16 v[86:89], v[150:153], v[182:185], v[86:89]
	v_mfma_f32_16x16x32_bf16 v[82:85], v[158:161], v[182:185], v[82:85]
	v_mfma_f32_16x16x32_bf16 v[70:73], v[150:153], v[226:229], v[70:73]
	v_mfma_f32_16x16x32_bf16 v[66:69], v[158:161], v[226:229], v[66:69]
	s_barrier
; #define PG8_STAGE(bufoff, gbase, voff) do { _Pragma("unroll") for (int _i = 0; _i < 2; ++_i) \
;         __builtin_amdgcn_global_load_lds((const unsigned*)((const char*)(gbase) + (voff)[_i]), (PG8_LAS unsigned*)(lds + (bufoff) + ldsw + _i * 8192), 16, 0, 0); } while (0)
; #define PG8_LDA(dst, b, h) do { _Pragma("unroll") for (int m = 0; m < 4; ++m) _Pragma("unroll") for (int k = 0; k < 2; ++k) dst[m][k] = *(const PG8_LAS bf16x8*)(lds + PG8_SA(b, h) + aoff + m * 2048 + k * 1024); } while (0)
; #define PG8_MMA(ai, bj, At, Bt) do { __builtin_amdgcn_s_setprio(1); _Pragma("unroll") for (int m = 0; m < 4; ++m) _Pragma("unroll") for (int n = 0; n < 2; ++n) _Pragma("unroll") for (int k = 0; k < 2; ++k) \
;         acc[ai][bj][m][n] = __builtin_amdgcn_mfma_f32_16x16x32_bf16(Bt[n][k], At[m][k], acc[ai][bj][m][n], 0, 0, 0); __builtin_amdgcn_s_setprio(0); } while (0)
; #define PG8_WAIT_V(n) asm volatile("s_waitcnt vmcnt(" #n ")" ::: "memory")
; #define PG8_WAIT_L(n) asm volatile("s_waitcnt lgkmcnt(" #n ")" ::: "memory")
; #define PG8_BAR __builtin_amdgcn_s_barrier()
; #define PG8_SCHED __builtin_amdgcn_sched_barrier(0)
; template <class Epi, class Sched, bool ALIGN_EPI = false, bool SP2 = false>
; __device__ __forceinline__ void gemm_phase(PG8_LAS unsigned char* lds, const Gemm g, const Sched& S, const Epi& E) {
;     ...
;             PG8_LDA(At, 1, 1); PG8_STAGE(PG8_SB(1, 0), b3, voffB); PG8_STAGE(PG8_SB(1, 1), b3 + hstepB, voffB); PG8_STAGE(PG8_SA(1, 0), a3, voffA);
;             PG8_WAIT_V(8); PG8_WAIT_L(0); PG8_BAR; PG8_MMA(1, 0, At, B0); PG8_MMA(1, 1, At, B1); PG8_BAR; PG8_SCHED;
;     ...
;         if constexpr (ALIGN_EPI) { if (wr == 0) PG8_BAR; }
	s_setprio 0
	s_add_u32 s46, s44, 0x8000
	s_addc_u32 s47, s45, 0
	s_add_i32 s55, s55, s0
	v_lshl_add_u64 v[230:231], s[46:47], 0, v[188:189]
	s_mov_b32 m0, s55
	ds_read_b128 v[162:165], v217 offset:49152
	ds_read_b128 v[166:169], v217 offset:50176
	ds_read_b128 v[170:173], v217 offset:51200
	ds_read_b128 v[174:177], v217 offset:52224
	ds_read_b128 v[178:181], v217 offset:53248
	ds_read_b128 v[182:185], v217 offset:54272
	ds_read_b128 v[222:225], v217 offset:55296
	ds_read_b128 v[226:229], v217 offset:56320
	global_load_lds_dwordx4 v[230:231], off
	s_add_i32 m0, s55, 0x2000
	s_add_u32 s44, s44, 0x9000
	v_lshl_add_u64 v[230:231], s[46:47], 0, v[192:193]
	s_addc_u32 s45, s45, 0
	s_add_i32 s46, s67, s0
	global_load_lds_dwordx4 v[230:231], off
	v_lshl_add_u64 v[230:231], s[44:45], 0, v[188:189]
	s_mov_b32 m0, s46
	s_nop 0
	global_load_lds_dwordx4 v[230:231], off
	v_lshl_add_u64 v[230:231], s[44:45], 0, v[192:193]
	s_add_i32 m0, s46, 0x2000
	s_nop 0
	global_load_lds_dwordx4 v[230:231], off
	v_lshl_add_u64 v[230:231], s[42:43], 0, v[186:187]
	s_mov_b32 m0, s56
	s_nop 0
	global_load_lds_dwordx4 v[230:231], off
	v_lshl_add_u64 v[230:231], s[42:43], 0, v[190:191]
	s_mov_b32 m0, s57
	s_nop 0
	global_load_lds_dwordx4 v[230:231], off
	s_waitcnt vmcnt(8)
	s_waitcnt lgkmcnt(0)
	s_setprio 1
	s_barrier
	v_mfma_f32_16x16x32_bf16 v[62:65], v[98:101], v[162:165], v[62:65]
	v_mfma_f32_16x16x32_bf16 v[58:61], v[122:125], v[162:165], v[58:61]
	v_mfma_f32_16x16x32_bf16 v[46:49], v[98:101], v[170:173], v[46:49]
	v_mfma_f32_16x16x32_bf16 v[42:45], v[122:125], v[170:173], v[42:45]
	v_mfma_f32_16x16x32_bf16 v[30:33], v[98:101], v[178:181], v[30:33]
	v_mfma_f32_16x16x32_bf16 v[26:29], v[122:125], v[178:181], v[26:29]
	v_mfma_f32_16x16x32_bf16 v[14:17], v[98:101], v[222:225], v[14:17]
	v_mfma_f32_16x16x32_bf16 v[10:13], v[122:125], v[222:225], v[10:13]
	v_mfma_f32_16x16x32_bf16 v[62:65], v[102:105], v[166:169], v[62:65]
	v_mfma_f32_16x16x32_bf16 v[58:61], v[126:129], v[166:169], v[58:61]
	v_mfma_f32_16x16x32_bf16 v[46:49], v[102:105], v[174:177], v[46:49]
	v_mfma_f32_16x16x32_bf16 v[42:45], v[126:129], v[174:177], v[42:45]
	v_mfma_f32_16x16x32_bf16 v[30:33], v[102:105], v[182:185], v[30:33]
	v_mfma_f32_16x16x32_bf16 v[26:29], v[126:129], v[182:185], v[26:29]
	v_mfma_f32_16x16x32_bf16 v[14:17], v[102:105], v[226:229], v[14:17]
	v_mfma_f32_16x16x32_bf16 v[10:13], v[126:129], v[226:229], v[10:13]
	s_setprio 0
	s_setprio 1
	v_mfma_f32_16x16x32_bf16 v[54:57], v[146:149], v[162:165], v[54:57]
	v_mfma_f32_16x16x32_bf16 v[50:53], v[154:157], v[162:165], v[50:53]
	v_mfma_f32_16x16x32_bf16 v[38:41], v[146:149], v[170:173], v[38:41]
	v_mfma_f32_16x16x32_bf16 v[34:37], v[154:157], v[170:173], v[34:37]
	v_mfma_f32_16x16x32_bf16 v[22:25], v[146:149], v[178:181], v[22:25]
	v_mfma_f32_16x16x32_bf16 v[18:21], v[154:157], v[178:181], v[18:21]
	v_mfma_f32_16x16x32_bf16 v[6:9], v[146:149], v[222:225], v[6:9]
	v_mfma_f32_16x16x32_bf16 v[2:5], v[154:157], v[222:225], v[2:5]
	v_mfma_f32_16x16x32_bf16 v[54:57], v[150:153], v[166:169], v[54:57]
	v_mfma_f32_16x16x32_bf16 v[50:53], v[158:161], v[166:169], v[50:53]
	v_mfma_f32_16x16x32_bf16 v[38:41], v[150:153], v[174:177], v[38:41]
	v_mfma_f32_16x16x32_bf16 v[34:37], v[158:161], v[174:177], v[34:37]
	v_mfma_f32_16x16x32_bf16 v[22:25], v[150:153], v[182:185], v[22:25]
	v_mfma_f32_16x16x32_bf16 v[18:21], v[158:161], v[182:185], v[18:21]
	v_mfma_f32_16x16x32_bf16 v[6:9], v[150:153], v[226:229], v[6:9]
	v_mfma_f32_16x16x32_bf16 v[2:5], v[158:161], v[226:229], v[2:5]
	s_barrier
	s_setprio 0
	s_add_i32 s54, s54, 2
	s_add_u32 s36, s36, 0x10000
	s_addc_u32 s37, s37, 0
	s_add_u32 s52, s52, 0x10000
	s_addc_u32 s53, s53, 0
	s_cmp_gt_u32 s54, 61
	s_cbranch_scc0 .LBB0_682
	s_and_b64 vcc, exec, s[18:19]
	s_cbranch_vccz .LBB0_685
	s_barrier

; #define PG8_STAGE(bufoff, gbase, voff) do { _Pragma("unroll") for (int _i = 0; _i < 2; ++_i) \
;         __builtin_amdgcn_global_load_lds((const unsigned*)((const char*)(gbase) + (voff)[_i]), (PG8_LAS unsigned*)(lds + (bufoff) + ldsw + _i * 8192), 16, 0, 0); } while (0)
; #define PG8_LDA(dst, b, h) do { _Pragma("unroll") for (int m = 0; m < 4; ++m) _Pragma("unroll") for (int k = 0; k < 2; ++k) dst[m][k] = *(const PG8_LAS bf16x8*)(lds + PG8_SA(b, h) + aoff + m * 2048 + k * 1024); } while (0)
; #define PG8_LDB(dst, b, h) do { _Pragma("unroll") for (int n = 0; n < 2; ++n) _Pragma("unroll") for (int k = 0; k < 2; ++k) dst[n][k] = *(const PG8_LAS bf16x8*)(lds + PG8_SB(b, h) + boff + n * 2048 + k * 1024); } while (0)
; #define PG8_MMA(ai, bj, At, Bt) do { __builtin_amdgcn_s_setprio(1); _Pragma("unroll") for (int m = 0; m < 4; ++m) _Pragma("unroll") for (int n = 0; n < 2; ++n) _Pragma("unroll") for (int k = 0; k < 2; ++k) \
;         acc[ai][bj][m][n] = __builtin_amdgcn_mfma_f32_16x16x32_bf16(Bt[n][k], At[m][k], acc[ai][bj][m][n], 0, 0, 0); __builtin_amdgcn_s_setprio(0); } while (0)
; #define PG8_WAIT_V(n) asm volatile("s_waitcnt vmcnt(" #n ")" ::: "memory")
; #define PG8_WAIT_L(n) asm volatile("s_waitcnt lgkmcnt(" #n ")" ::: "memory")
; #define PG8_BAR __builtin_amdgcn_s_barrier()
; #define PG8_SCHED __builtin_amdgcn_sched_barrier(0)
; template <class Epi, class Sched, bool ALIGN_EPI = false, bool SP2 = false>
; __device__ __forceinline__ void gemm_phase(PG8_LAS unsigned char* lds, const Gemm g, const Sched& S, const Epi& E) {
;     ...
;             const bool last = (t == nt - 2);
;             const char* a1 = cA + (size_t)(t + 1) * kstep;
;             const char* a2 = last ? nA : cA + (size_t)(t + 2) * kstep; const char* b2 = last ? nB : cB + (size_t)(t + 2) * kstep;
;             const char* a3 = a2 + kstep; const char* b3 = b2 + kstep;
;             if (last && has_next) S.a_ready(nxt);
;             if constexpr (SP2) {
;             PG8_LDB(B0, 0, 0); PG8_LDB(B1, 0, 1); PG8_SCHED; PG8_LDA(At, 0, 0); PG8_STAGE(PG8_SA(1, 1), a1 + hstep, voffA);
;             PG8_WAIT_V(8); PG8_WAIT_L(0); PG8_BAR; PG8_MMA(0, 0, At, B0); PG8_MMA(0, 1, At, B1); PG8_BAR; PG8_SCHED;
;             PG8_LDA(At, 0, 1); PG8_STAGE(PG8_SB(0, 0), b2, voffB); PG8_STAGE(PG8_SB(0, 1), b2 + hstepB, voffB); PG8_STAGE(PG8_SA(0, 0), a2, voffA);
.LBB0_726:
	ds_read_b128 v[130:133], v209
	ds_read_b128 v[134:137], v209 offset:1024
	ds_read_b128 v[138:141], v209 offset:2048
	ds_read_b128 v[142:145], v209 offset:3072
	ds_read_b128 v[146:149], v210
	ds_read_b128 v[150:153], v210 offset:1024
	ds_read_b128 v[154:157], v210 offset:2048
	ds_read_b128 v[158:161], v210 offset:3072
	s_add_u32 s54, s50, 0x4000
	s_addc_u32 s55, s51, 0
	s_cmp_eq_u32 s53, 60
	s_cselect_b32 s68, s29, s54
	s_cselect_b32 s69, s27, s55
	s_cselect_b32 s66, s47, s49
	s_cselect_b32 s67, s37, s52
	s_add_u32 s64, s68, 0x8000
	s_addc_u32 s65, s69, 0
	v_lshl_add_u64 v[206:207], s[50:51], 0, v[198:199]
	s_add_i32 m0, s1, 0xc000
	ds_read_b128 v[162:165], v211
	ds_read_b128 v[166:169], v211 offset:1024
	ds_read_b128 v[170:173], v211 offset:2048
	ds_read_b128 v[174:177], v211 offset:3072
	ds_read_b128 v[178:181], v211 offset:4096
	ds_read_b128 v[182:185], v211 offset:5120
	ds_read_b128 v[224:227], v211 offset:6144
	ds_read_b128 v[228:231], v211 offset:7168
	global_load_lds_dwordx4 v[206:207], off
	v_lshl_add_u64 v[206:207], s[50:51], 0, v[200:201]
	s_add_i32 m0, s1, 0xe000
	s_nop 0
	global_load_lds_dwordx4 v[206:207], off
	s_waitcnt vmcnt(8)
	s_waitcnt lgkmcnt(0)
	s_setprio 1
	s_barrier
	v_mfma_f32_16x16x32_bf16 v[126:129], v[130:133], v[162:165], v[126:129]
	v_mfma_f32_16x16x32_bf16 v[122:125], v[138:141], v[162:165], v[122:125]
	v_mfma_f32_16x16x32_bf16 v[110:113], v[130:133], v[170:173], v[110:113]
	v_mfma_f32_16x16x32_bf16 v[106:109], v[138:141], v[170:173], v[106:109]
	v_mfma_f32_16x16x32_bf16 v[94:97], v[130:133], v[178:181], v[94:97]
	v_mfma_f32_16x16x32_bf16 v[90:93], v[138:141], v[178:181], v[90:93]
	v_mfma_f32_16x16x32_bf16 v[78:81], v[130:133], v[224:227], v[78:81]
	v_mfma_f32_16x16x32_bf16 v[74:77], v[138:141], v[224:227], v[74:77]
	v_mfma_f32_16x16x32_bf16 v[126:129], v[134:137], v[166:169], v[126:129]
	v_mfma_f32_16x16x32_bf16 v[122:125], v[142:145], v[166:169], v[122:125]
	v_mfma_f32_16x16x32_bf16 v[110:113], v[134:137], v[174:177], v[110:113]
	v_mfma_f32_16x16x32_bf16 v[106:109], v[142:145], v[174:177], v[106:109]
	v_mfma_f32_16x16x32_bf16 v[94:97], v[134:137], v[182:185], v[94:97]
	v_mfma_f32_16x16x32_bf16 v[90:93], v[142:145], v[182:185], v[90:93]
	v_mfma_f32_16x16x32_bf16 v[78:81], v[134:137], v[228:231], v[78:81]
	v_mfma_f32_16x16x32_bf16 v[74:77], v[142:145], v[228:231], v[74:77]
	s_setprio 0
	s_setprio 1
	v_mfma_f32_16x16x32_bf16 v[118:121], v[146:149], v[162:165], v[118:121]
	v_mfma_f32_16x16x32_bf16 v[114:117], v[154:157], v[162:165], v[114:117]
	v_mfma_f32_16x16x32_bf16 v[102:105], v[146:149], v[170:173], v[102:105]
	v_mfma_f32_16x16x32_bf16 v[98:101], v[154:157], v[170:173], v[98:101]
	v_mfma_f32_16x16x32_bf16 v[86:89], v[146:149], v[178:181], v[86:89]
	v_mfma_f32_16x16x32_bf16 v[82:85], v[154:157], v[178:181], v[82:85]
	v_mfma_f32_16x16x32_bf16 v[70:73], v[146:149], v[224:227], v[70:73]
	v_mfma_f32_16x16x32_bf16 v[66:69], v[154:157], v[224:227], v[66:69]
	v_mfma_f32_16x16x32_bf16 v[118:121], v[150:153], v[166:169], v[118:121]
	v_mfma_f32_16x16x32_bf16 v[114:117], v[158:161], v[166:169], v[114:117]
	v_mfma_f32_16x16x32_bf16 v[102:105], v[150:153], v[174:177], v[102:105]
	v_mfma_f32_16x16x32_bf16 v[98:101], v[158:161], v[174:177], v[98:101]
	v_mfma_f32_16x16x32_bf16 v[86:89], v[150:153], v[182:185], v[86:89]
	v_mfma_f32_16x16x32_bf16 v[82:85], v[158:161], v[182:185], v[82:85]
	v_mfma_f32_16x16x32_bf16 v[70:73], v[150:153], v[228:231], v[70:73]
	v_mfma_f32_16x16x32_bf16 v[66:69], v[158:161], v[228:231], v[66:69]
	s_barrier
	s_setprio 0
	s_add_i32 s54, s74, s0
	v_lshl_add_u64 v[206:207], s[66:67], 0, v[188:189]
	s_mov_b32 m0, s54
	ds_read_b128 v[162:165], v211 offset:16384
	ds_read_b128 v[166:169], v211 offset:17408
	ds_read_b128 v[170:173], v211 offset:18432
	ds_read_b128 v[174:177], v211 offset:19456
	ds_read_b128 v[178:181], v211 offset:20480
	ds_read_b128 v[182:185], v211 offset:21504
	ds_read_b128 v[224:227], v211 offset:22528
	ds_read_b128 v[228:231], v211 offset:23552
	global_load_lds_dwordx4 v[206:207], off
	s_add_i32 m0, s54, 0x2000
	s_add_u32 s54, s66, 0x1000
	v_lshl_add_u64 v[206:207], s[66:67], 0, v[192:193]
	s_addc_u32 s55, s67, 0
	s_add_i32 s89, s75, s0
	global_load_lds_dwordx4 v[206:207], off
	v_lshl_add_u64 v[206:207], s[54:55], 0, v[188:189]
	s_mov_b32 m0, s89
	s_nop 0
	global_load_lds_dwordx4 v[206:207], off
	v_lshl_add_u64 v[206:207], s[54:55], 0, v[192:193]
	s_add_i32 m0, s89, 0x2000
	s_nop 0
	global_load_lds_dwordx4 v[206:207], off
	v_lshl_add_u64 v[206:207], s[68:69], 0, v[186:187]
	s_mov_b32 m0, s1
	s_nop 0
	global_load_lds_dwordx4 v[206:207], off
	v_lshl_add_u64 v[206:207], s[68:69], 0, v[190:191]
	s_mov_b32 m0, s3
	s_nop 0
	global_load_lds_dwordx4 v[206:207], off
	s_waitcnt vmcnt(8)
	s_waitcnt lgkmcnt(0)
	s_setprio 1
	s_barrier
; #define PG8_STAGE(bufoff, gbase, voff) do { _Pragma("unroll") for (int _i = 0; _i < 2; ++_i) \
;         __builtin_amdgcn_global_load_lds((const unsigned*)((const char*)(gbase) + (voff)[_i]), (PG8_LAS unsigned*)(lds + (bufoff) + ldsw + _i * 8192), 16, 0, 0); } while (0)
; #define PG8_LDA(dst, b, h) do { _Pragma("unroll") for (int m = 0; m < 4; ++m) _Pragma("unroll") for (int k = 0; k < 2; ++k) dst[m][k] = *(const PG8_LAS bf16x8*)(lds + PG8_SA(b, h) + aoff + m * 2048 + k * 1024); } while (0)
; #define PG8_LDB(dst, b, h) do { _Pragma("unroll") for (int n = 0; n < 2; ++n) _Pragma("unroll") for (int k = 0; k < 2; ++k) dst[n][k] = *(const PG8_LAS bf16x8*)(lds + PG8_SB(b, h) + boff + n * 2048 + k * 1024); } while (0)
; #define PG8_MMA(ai, bj, At, Bt) do { __builtin_amdgcn_s_setprio(1); _Pragma("unroll") for (int m = 0; m < 4; ++m) _Pragma("unroll") for (int n = 0; n < 2; ++n) _Pragma("unroll") for (int k = 0; k < 2; ++k) \
;         acc[ai][bj][m][n] = __builtin_amdgcn_mfma_f32_16x16x32_bf16(Bt[n][k], At[m][k], acc[ai][bj][m][n], 0, 0, 0); __builtin_amdgcn_s_setprio(0); } while (0)
; #define PG8_WAIT_V(n) asm volatile("s_waitcnt vmcnt(" #n ")" ::: "memory")
; #define PG8_WAIT_L(n) asm volatile("s_waitcnt lgkmcnt(" #n ")" ::: "memory")
; #define PG8_BAR __builtin_amdgcn_s_barrier()
; #define PG8_SCHED __builtin_amdgcn_sched_barrier(0)
; template <class Epi, class Sched, bool ALIGN_EPI = false, bool SP2 = false>
; __device__ __forceinline__ void gemm_phase(PG8_LAS unsigned char* lds, const Gemm g, const Sched& S, const Epi& E) {
;     ...
;             PG8_LDA(At, 0, 1); PG8_STAGE(PG8_SB(0, 0), b2, voffB); PG8_STAGE(PG8_SB(0, 1), b2 + hstepB, voffB); PG8_STAGE(PG8_SA(0, 0), a2, voffA);
;             PG8_WAIT_V(8); PG8_WAIT_L(0); PG8_BAR; PG8_MMA(1, 0, At, B0); PG8_MMA(1, 1, At, B1); PG8_BAR; PG8_SCHED;
;             PG8_LDB(B0, 1, 0); PG8_LDB(B1, 1, 1); PG8_SCHED; PG8_LDA(At, 1, 0); PG8_STAGE(PG8_SA(0, 1), a2 + hstep, voffA);
;             PG8_WAIT_V(8); PG8_WAIT_L(0); PG8_BAR; PG8_MMA(0, 0, At, B0); PG8_MMA(0, 1, At, B1); PG8_BAR; PG8_SCHED;
	v_mfma_f32_16x16x32_bf16 v[62:65], v[130:133], v[162:165], v[62:65]
	v_mfma_f32_16x16x32_bf16 v[58:61], v[138:141], v[162:165], v[58:61]
	v_mfma_f32_16x16x32_bf16 v[46:49], v[130:133], v[170:173], v[46:49]
	v_mfma_f32_16x16x32_bf16 v[42:45], v[138:141], v[170:173], v[42:45]
	v_mfma_f32_16x16x32_bf16 v[30:33], v[130:133], v[178:181], v[30:33]
	v_mfma_f32_16x16x32_bf16 v[26:29], v[138:141], v[178:181], v[26:29]
	v_mfma_f32_16x16x32_bf16 v[14:17], v[130:133], v[224:227], v[14:17]
	v_mfma_f32_16x16x32_bf16 v[10:13], v[138:141], v[224:227], v[10:13]
	v_mfma_f32_16x16x32_bf16 v[62:65], v[134:137], v[166:169], v[62:65]
	v_mfma_f32_16x16x32_bf16 v[58:61], v[142:145], v[166:169], v[58:61]
	v_mfma_f32_16x16x32_bf16 v[46:49], v[134:137], v[174:177], v[46:49]
	v_mfma_f32_16x16x32_bf16 v[42:45], v[142:145], v[174:177], v[42:45]
	v_mfma_f32_16x16x32_bf16 v[30:33], v[134:137], v[182:185], v[30:33]
	v_mfma_f32_16x16x32_bf16 v[26:29], v[142:145], v[182:185], v[26:29]
	v_mfma_f32_16x16x32_bf16 v[14:17], v[134:137], v[228:231], v[14:17]
	v_mfma_f32_16x16x32_bf16 v[10:13], v[142:145], v[228:231], v[10:13]
	s_setprio 0
	s_setprio 1
	v_mfma_f32_16x16x32_bf16 v[54:57], v[146:149], v[162:165], v[54:57]
	v_mfma_f32_16x16x32_bf16 v[50:53], v[154:157], v[162:165], v[50:53]
	v_mfma_f32_16x16x32_bf16 v[38:41], v[146:149], v[170:173], v[38:41]
	v_mfma_f32_16x16x32_bf16 v[34:37], v[154:157], v[170:173], v[34:37]
	v_mfma_f32_16x16x32_bf16 v[22:25], v[146:149], v[178:181], v[22:25]
	v_mfma_f32_16x16x32_bf16 v[18:21], v[154:157], v[178:181], v[18:21]
	v_mfma_f32_16x16x32_bf16 v[6:9], v[146:149], v[224:227], v[6:9]
	v_mfma_f32_16x16x32_bf16 v[2:5], v[154:157], v[224:227], v[2:5]
	v_mfma_f32_16x16x32_bf16 v[54:57], v[150:153], v[166:169], v[54:57]
	v_mfma_f32_16x16x32_bf16 v[50:53], v[158:161], v[166:169], v[50:53]
	v_mfma_f32_16x16x32_bf16 v[38:41], v[150:153], v[174:177], v[38:41]
	v_mfma_f32_16x16x32_bf16 v[34:37], v[158:161], v[174:177], v[34:37]
	v_mfma_f32_16x16x32_bf16 v[22:25], v[150:153], v[182:185], v[22:25]
	v_mfma_f32_16x16x32_bf16 v[18:21], v[158:161], v[182:185], v[18:21]
	v_mfma_f32_16x16x32_bf16 v[6:9], v[150:153], v[228:231], v[6:9]
	v_mfma_f32_16x16x32_bf16 v[2:5], v[158:161], v[228:231], v[2:5]
	s_barrier
	s_setprio 0
	s_add_i32 s89, 0, 0x18000
	s_add_i32 s90, 0, 0x1c000
	v_add_u32_e32 v142, s89, v214
	v_add_u32_e32 v158, s90, v214
	ds_read_b128 v[130:133], v142
	ds_read_b128 v[134:137], v142 offset:1024
	ds_read_b128 v[138:141], v142 offset:2048
	ds_read_b128 v[142:145], v142 offset:3072
	ds_read_b128 v[146:149], v158
	ds_read_b128 v[150:153], v158 offset:1024
	ds_read_b128 v[154:157], v158 offset:2048
	ds_read_b128 v[158:161], v158 offset:3072
	s_add_u32 s54, s68, 0x4000
	s_addc_u32 s55, s69, 0
	s_mov_b32 m0, s56
	v_lshl_add_u64 v[206:207], s[54:55], 0, v[186:187]
	ds_read_b128 v[162:165], v211 offset:32768
	ds_read_b128 v[166:169], v211 offset:33792
	ds_read_b128 v[170:173], v211 offset:34816
	ds_read_b128 v[174:177], v211 offset:35840
	ds_read_b128 v[178:181], v211 offset:36864
	ds_read_b128 v[182:185], v211 offset:37888
	ds_read_b128 v[224:227], v211 offset:38912
	ds_read_b128 v[228:231], v211 offset:39936
	global_load_lds_dwordx4 v[206:207], off
	v_lshl_add_u64 v[206:207], s[54:55], 0, v[190:191]
	s_mov_b32 m0, s57
	s_nop 0
	global_load_lds_dwordx4 v[206:207], off
	s_waitcnt vmcnt(8)
	s_waitcnt lgkmcnt(0)
	s_setprio 1
	s_barrier
	v_mfma_f32_16x16x32_bf16 v[126:129], v[130:133], v[162:165], v[126:129]
	v_mfma_f32_16x16x32_bf16 v[122:125], v[138:141], v[162:165], v[122:125]
	v_mfma_f32_16x16x32_bf16 v[110:113], v[130:133], v[170:173], v[110:113]
	v_mfma_f32_16x16x32_bf16 v[106:109], v[138:141], v[170:173], v[106:109]
	v_mfma_f32_16x16x32_bf16 v[94:97], v[130:133], v[178:181], v[94:97]
	v_mfma_f32_16x16x32_bf16 v[90:93], v[138:141], v[178:181], v[90:93]
	v_mfma_f32_16x16x32_bf16 v[78:81], v[130:133], v[224:227], v[78:81]
	v_mfma_f32_16x16x32_bf16 v[74:77], v[138:141], v[224:227], v[74:77]
	v_mfma_f32_16x16x32_bf16 v[126:129], v[134:137], v[166:169], v[126:129]
	v_mfma_f32_16x16x32_bf16 v[122:125], v[142:145], v[166:169], v[122:125]
	v_mfma_f32_16x16x32_bf16 v[110:113], v[134:137], v[174:177], v[110:113]
	v_mfma_f32_16x16x32_bf16 v[106:109], v[142:145], v[174:177], v[106:109]
	v_mfma_f32_16x16x32_bf16 v[94:97], v[134:137], v[182:185], v[94:97]
	v_mfma_f32_16x16x32_bf16 v[90:93], v[142:145], v[182:185], v[90:93]
	v_mfma_f32_16x16x32_bf16 v[78:81], v[134:137], v[228:231], v[78:81]
	v_mfma_f32_16x16x32_bf16 v[74:77], v[142:145], v[228:231], v[74:77]
	s_setprio 0
	s_setprio 1
	v_mfma_f32_16x16x32_bf16 v[118:121], v[146:149], v[162:165], v[118:121]
	v_mfma_f32_16x16x32_bf16 v[114:117], v[154:157], v[162:165], v[114:117]
	v_mfma_f32_16x16x32_bf16 v[102:105], v[146:149], v[170:173], v[102:105]
	v_mfma_f32_16x16x32_bf16 v[98:101], v[154:157], v[170:173], v[98:101]
	v_mfma_f32_16x16x32_bf16 v[86:89], v[146:149], v[178:181], v[86:89]
	v_mfma_f32_16x16x32_bf16 v[82:85], v[154:157], v[178:181], v[82:85]
	v_mfma_f32_16x16x32_bf16 v[70:73], v[146:149], v[224:227], v[70:73]
	v_mfma_f32_16x16x32_bf16 v[66:69], v[154:157], v[224:227], v[66:69]
	v_mfma_f32_16x16x32_bf16 v[118:121], v[150:153], v[166:169], v[118:121]
	v_mfma_f32_16x16x32_bf16 v[114:117], v[158:161], v[166:169], v[114:117]
	v_mfma_f32_16x16x32_bf16 v[102:105], v[150:153], v[174:177], v[102:105]
	v_mfma_f32_16x16x32_bf16 v[98:101], v[158:161], v[174:177], v[98:101]
	v_mfma_f32_16x16x32_bf16 v[86:89], v[150:153], v[182:185], v[86:89]
	v_mfma_f32_16x16x32_bf16 v[82:85], v[158:161], v[182:185], v[82:85]
	v_mfma_f32_16x16x32_bf16 v[70:73], v[150:153], v[228:231], v[70:73]
	v_mfma_f32_16x16x32_bf16 v[66:69], v[158:161], v[228:231], v[66:69]
	s_barrier
; #define PG8_STAGE(bufoff, gbase, voff) do { _Pragma("unroll") for (int _i = 0; _i < 2; ++_i) \
;         __builtin_amdgcn_global_load_lds((const unsigned*)((const char*)(gbase) + (voff)[_i]), (PG8_LAS unsigned*)(lds + (bufoff) + ldsw + _i * 8192), 16, 0, 0); } while (0)
; #define PG8_LDA(dst, b, h) do { _Pragma("unroll") for (int m = 0; m < 4; ++m) _Pragma("unroll") for (int k = 0; k < 2; ++k) dst[m][k] = *(const PG8_LAS bf16x8*)(lds + PG8_SA(b, h) + aoff + m * 2048 + k * 1024); } while (0)
; #define PG8_MMA(ai, bj, At, Bt) do { __builtin_amdgcn_s_setprio(1); _Pragma("unroll") for (int m = 0; m < 4; ++m) _Pragma("unroll") for (int n = 0; n < 2; ++n) _Pragma("unroll") for (int k = 0; k < 2; ++k) \
;         acc[ai][bj][m][n] = __builtin_amdgcn_mfma_f32_16x16x32_bf16(Bt[n][k], At[m][k], acc[ai][bj][m][n], 0, 0, 0); __builtin_amdgcn_s_setprio(0); } while (0)
; #define PG8_WAIT_V(n) asm volatile("s_waitcnt vmcnt(" #n ")" ::: "memory")
; #define PG8_WAIT_L(n) asm volatile("s_waitcnt lgkmcnt(" #n ")" ::: "memory")
; #define PG8_BAR __builtin_amdgcn_s_barrier()
; #define PG8_SCHED __builtin_amdgcn_sched_barrier(0)
; template <class Epi, class Sched, bool ALIGN_EPI = false, bool SP2 = false>
; __device__ __forceinline__ void gemm_phase(PG8_LAS unsigned char* lds, const Gemm g, const Sched& S, const Epi& E) {
;     ...
;             PG8_LDA(At, 1, 1); PG8_STAGE(PG8_SB(1, 0), b3, voffB); PG8_STAGE(PG8_SB(1, 1), b3 + hstepB, voffB); PG8_STAGE(PG8_SA(1, 0), a3, voffA);
;             PG8_WAIT_V(8); PG8_WAIT_L(0); PG8_BAR; PG8_MMA(1, 0, At, B0); PG8_MMA(1, 1, At, B1); PG8_BAR; PG8_SCHED;
;     ...
;         if constexpr (ALIGN_EPI) { if (wr == 0) PG8_BAR; }
	s_setprio 0
	s_add_u32 s54, s66, 0x8000
	s_addc_u32 s55, s67, 0
	s_add_i32 s68, s89, s0
	v_lshl_add_u64 v[206:207], s[54:55], 0, v[188:189]
	s_mov_b32 m0, s68
	ds_read_b128 v[162:165], v211 offset:49152
	ds_read_b128 v[166:169], v211 offset:50176
	ds_read_b128 v[170:173], v211 offset:51200
	ds_read_b128 v[174:177], v211 offset:52224
	ds_read_b128 v[178:181], v211 offset:53248
	ds_read_b128 v[182:185], v211 offset:54272
	ds_read_b128 v[224:227], v211 offset:55296
	ds_read_b128 v[228:231], v211 offset:56320
	global_load_lds_dwordx4 v[206:207], off
	s_add_i32 m0, s68, 0x2000
	v_lshl_add_u64 v[206:207], s[54:55], 0, v[192:193]
	s_add_u32 s54, s66, 0x9000
	s_addc_u32 s55, s67, 0
	s_add_i32 s66, s90, s0
	global_load_lds_dwordx4 v[206:207], off
	v_lshl_add_u64 v[206:207], s[54:55], 0, v[188:189]
	s_mov_b32 m0, s66
	s_nop 0
	global_load_lds_dwordx4 v[206:207], off
	v_lshl_add_u64 v[206:207], s[54:55], 0, v[192:193]
	s_add_i32 m0, s66, 0x2000
	s_nop 0
	global_load_lds_dwordx4 v[206:207], off
	v_lshl_add_u64 v[206:207], s[64:65], 0, v[186:187]
	s_mov_b32 m0, s71
	s_nop 0
	global_load_lds_dwordx4 v[206:207], off
	v_lshl_add_u64 v[206:207], s[64:65], 0, v[190:191]
	s_mov_b32 m0, s72
	s_nop 0
	global_load_lds_dwordx4 v[206:207], off
	s_waitcnt vmcnt(8)
	s_waitcnt lgkmcnt(0)
	s_setprio 1
	s_barrier
	v_mfma_f32_16x16x32_bf16 v[62:65], v[130:133], v[162:165], v[62:65]
	v_mfma_f32_16x16x32_bf16 v[58:61], v[138:141], v[162:165], v[58:61]
	v_mfma_f32_16x16x32_bf16 v[46:49], v[130:133], v[170:173], v[46:49]
	v_mfma_f32_16x16x32_bf16 v[42:45], v[138:141], v[170:173], v[42:45]
	v_mfma_f32_16x16x32_bf16 v[30:33], v[130:133], v[178:181], v[30:33]
	v_mfma_f32_16x16x32_bf16 v[26:29], v[138:141], v[178:181], v[26:29]
	v_mfma_f32_16x16x32_bf16 v[14:17], v[130:133], v[224:227], v[14:17]
	v_mfma_f32_16x16x32_bf16 v[10:13], v[138:141], v[224:227], v[10:13]
	v_mfma_f32_16x16x32_bf16 v[62:65], v[134:137], v[166:169], v[62:65]
	v_mfma_f32_16x16x32_bf16 v[58:61], v[142:145], v[166:169], v[58:61]
	v_mfma_f32_16x16x32_bf16 v[46:49], v[134:137], v[174:177], v[46:49]
	v_mfma_f32_16x16x32_bf16 v[42:45], v[142:145], v[174:177], v[42:45]
	v_mfma_f32_16x16x32_bf16 v[30:33], v[134:137], v[182:185], v[30:33]
	v_mfma_f32_16x16x32_bf16 v[26:29], v[142:145], v[182:185], v[26:29]
	v_mfma_f32_16x16x32_bf16 v[14:17], v[134:137], v[228:231], v[14:17]
	v_mfma_f32_16x16x32_bf16 v[10:13], v[142:145], v[228:231], v[10:13]
	s_setprio 0
	s_setprio 1
	v_mfma_f32_16x16x32_bf16 v[54:57], v[146:149], v[162:165], v[54:57]
	v_mfma_f32_16x16x32_bf16 v[50:53], v[154:157], v[162:165], v[50:53]
	v_mfma_f32_16x16x32_bf16 v[38:41], v[146:149], v[170:173], v[38:41]
	v_mfma_f32_16x16x32_bf16 v[34:37], v[154:157], v[170:173], v[34:37]
	v_mfma_f32_16x16x32_bf16 v[22:25], v[146:149], v[178:181], v[22:25]
	v_mfma_f32_16x16x32_bf16 v[18:21], v[154:157], v[178:181], v[18:21]
	v_mfma_f32_16x16x32_bf16 v[6:9], v[146:149], v[224:227], v[6:9]
	v_mfma_f32_16x16x32_bf16 v[2:5], v[154:157], v[224:227], v[2:5]
	v_mfma_f32_16x16x32_bf16 v[54:57], v[150:153], v[166:169], v[54:57]
	v_mfma_f32_16x16x32_bf16 v[50:53], v[158:161], v[166:169], v[50:53]
	v_mfma_f32_16x16x32_bf16 v[38:41], v[150:153], v[174:177], v[38:41]
	v_mfma_f32_16x16x32_bf16 v[34:37], v[158:161], v[174:177], v[34:37]
	v_mfma_f32_16x16x32_bf16 v[22:25], v[150:153], v[182:185], v[22:25]
	v_mfma_f32_16x16x32_bf16 v[18:21], v[158:161], v[182:185], v[18:21]
	v_mfma_f32_16x16x32_bf16 v[6:9], v[150:153], v[228:231], v[6:9]
	v_mfma_f32_16x16x32_bf16 v[2:5], v[158:161], v[228:231], v[2:5]
	s_barrier
	s_setprio 0
	s_add_i32 s53, s53, 2
	s_add_u32 s50, s50, 0x10000
	s_addc_u32 s51, s51, 0
	s_add_u32 s49, s49, 0x10000
	s_addc_u32 s52, s52, 0
	s_cmp_gt_u32 s53, 61
	s_cbranch_scc0 .LBB0_726
	s_and_b64 vcc, exec, s[20:21]
	s_cbranch_vccz .LBB0_729
	s_barrier
